# residual epilogue (out-proj + FFN-down): 16 serialized xb row loads per thread issued together at epilogue start into free fragment registers; per-row vmcnt waits (which also drained stores) removed
# speedup vs baseline: 1.0173x; 1.0055x over previous
; __device__ __forceinline__ unsigned cvt_pk_bf16(float lo, float hi) { unsigned r; asm volatile("v_cvt_pk_bf16_f32 %0, %1, %2" : "=v"(r) : "v"(lo), "v"(hi)); return r; }
; __device__ __forceinline__ void UNPACK8(const u32x4 q, float (&f)[8]) { f[0] = bflo(q.x); f[1] = bfhi(q.x); f[2] = bflo(q.y); f[3] = bfhi(q.y); f[4] = bflo(q.z); f[5] = bfhi(q.z); f[6] = bflo(q.w); f[7] = bfhi(q.w); }
; #define EPI_FOR_ROWS() _Pragma("unroll") for (int ai = 0; ai < 2; ++ai) _Pragma("unroll") for (int m = 0; m < 4; ++m)
;     __device__ __forceinline__ void operator()(const f32x4 (&acc)[2][2][4][2], const Unit& u, int wr, int wc, int fr, int fq) const {
;     ...
;         EPI_FOR_ROWS() {
;             const int row = row0 + ai * 128 + m * 16; float ss = 0.f;
; #pragma unroll
;             for (int bj = 0; bj < 2; ++bj) { const int col = col0 + bj * 128; const size_t off = (size_t)row * 1024 + col;
;                 const u32x4 xw = *(const u32x4*)(xb + off); float xo[8]; UNPACK8(xw, xo);
;                 const f32x4 x0 = (f32x4){xo[0], xo[1], xo[2], xo[3]} + acc[ai][bj][m][0], x1 = (f32x4){xo[4], xo[5], xo[6], xo[7]} + acc[ai][bj][m][1];
;                 ss += (x0[0] * x0[0] + x0[1] * x0[1]) + (x0[2] * x0[2] + x0[3] * x0[3]) + (x1[0] * x1[0] + x1[1] * x1[1]) + (x1[2] * x1[2] + x1[3] * x1[3]);
;                 u32x4 w; w.x = cvt_pk_bf16(x0[0], x0[1]); w.y = cvt_pk_bf16(x0[2], x0[3]); w.z = cvt_pk_bf16(x1[0], x1[1]); w.w = cvt_pk_bf16(x1[2], x1[3]);
;                 *(u32x4*)(xb + off) = w; }
;             ss += __shfl_xor(ss, 16); ss += __shfl_xor(ss, 32);
;             if (fq == 0) ssq[(size_t)row * 16 + u.pn * 4 + wc] = ss;
;         }
.LBB0_946:
	v_lshl_add_u32 v130, s65, 8, v136
	v_ashrrev_i32_e32 v131, 31, v130
	v_lshl_or_b32 v128, s64, 8, v137
	v_lshlrev_b64 v[144:145], 11, v[130:131]
	v_ashrrev_i32_e32 v129, 31, v128
	v_lshl_add_u64 v[144:145], s[22:23], 0, v[144:145]
	v_lshl_add_u64 v[148:149], v[128:129], 1, v[144:145]
	global_load_dwordx4 v[156:159], v[148:149], off
	global_load_dwordx4 v[166:169], v[148:149], off offset:256
	s_mov_b32 s38, 0x8000
	s_mov_b32 s39, 0
	v_lshl_add_u64 v[182:183], v[148:149], 0, s[38:39]
	global_load_dwordx4 v[178:181], v[182:183], off
	global_load_dwordx4 v[182:185], v[182:183], off offset:256
	s_mov_b32 s38, 0x10000
	s_mov_b32 s39, 0
	v_lshl_add_u64 v[190:191], v[148:149], 0, s[38:39]
	global_load_dwordx4 v[186:189], v[190:191], off
	global_load_dwordx4 v[190:193], v[190:191], off offset:256
	s_mov_b32 s38, 0x18000
	s_mov_b32 s39, 0
	v_lshl_add_u64 v[198:199], v[148:149], 0, s[38:39]
	global_load_dwordx4 v[194:197], v[198:199], off
	global_load_dwordx4 v[198:201], v[198:199], off offset:256
	s_mov_b32 s38, 0x40000
	s_mov_b32 s39, 0
	v_lshl_add_u64 v[214:215], v[148:149], 0, s[38:39]
	global_load_dwordx4 v[202:205], v[214:215], off
	global_load_dwordx4 v[214:217], v[214:215], off offset:256
	s_mov_b32 s38, 0x48000
	s_mov_b32 s39, 0
	v_lshl_add_u64 v[222:223], v[148:149], 0, s[38:39]
	global_load_dwordx4 v[218:221], v[222:223], off
	global_load_dwordx4 v[222:225], v[222:223], off offset:256
	s_mov_b32 s38, 0x50000
	s_mov_b32 s39, 0
	v_lshl_add_u64 v[230:231], v[148:149], 0, s[38:39]
	global_load_dwordx4 v[226:229], v[230:231], off
	global_load_dwordx4 v[230:233], v[230:231], off offset:256
	s_mov_b32 s38, 0x58000
	s_mov_b32 s39, 0
	v_lshl_add_u64 v[238:239], v[148:149], 0, s[38:39]
	global_load_dwordx4 v[234:237], v[238:239], off
	global_load_dwordx4 v[238:241], v[238:239], off offset:256
	s_waitcnt vmcnt(0)
	v_mov_b32_e32 v144, v156
	v_mov_b32_e32 v145, v157
	v_mov_b32_e32 v146, v158
	v_mov_b32_e32 v147, v159
	s_lshl_b32 s38, s64, 2
	s_ashr_i32 s39, s38, 31
	v_lshlrev_b32_e32 v150, 16, v144
	v_and_b32_e32 v151, 0xffff0000, v144
	v_lshlrev_b32_e32 v144, 16, v145
	v_and_b32_e32 v145, 0xffff0000, v145
	v_lshlrev_b32_e32 v152, 16, v146
	v_and_b32_e32 v153, 0xffff0000, v146
	v_lshlrev_b32_e32 v146, 16, v147
	v_and_b32_e32 v147, 0xffff0000, v147
	v_pk_add_f32 v[126:127], v[126:127], v[144:145]
	v_pk_add_f32 v[124:125], v[124:125], v[150:151]
	v_pk_add_f32 v[144:145], v[122:123], v[146:147]
	v_pk_add_f32 v[122:123], v[120:121], v[152:153]
	v_mul_f32_e32 v120, v125, v125
	v_mul_f32_e32 v121, v127, v127
	v_fmac_f32_e32 v120, v124, v124
	v_fmac_f32_e32 v121, v126, v126
	v_add_f32_e32 v120, v120, v121
	v_mul_f32_e32 v121, v123, v123
	v_fmac_f32_e32 v121, v122, v122
	v_add_f32_e32 v120, v121, v120
	v_mul_f32_e32 v121, v145, v145
	v_fmac_f32_e32 v121, v144, v144
	v_add_f32_e32 v143, v121, v120
	v_cvt_pk_bf16_f32 v120, v124, v125
	v_cvt_pk_bf16_f32 v121, v126, v127
	v_cvt_pk_bf16_f32 v122, v122, v123
	v_cvt_pk_bf16_f32 v123, v144, v145
	global_store_dwordx4 v[148:149], v[120:123], off
	s_nop 1
	v_mov_b32_e32 v120, v166
	v_mov_b32_e32 v121, v167
	v_mov_b32_e32 v122, v168
	v_mov_b32_e32 v123, v169
	v_lshlrev_b32_e32 v124, 16, v120
	v_and_b32_e32 v125, 0xffff0000, v120
	v_lshlrev_b32_e32 v120, 16, v121
	v_and_b32_e32 v121, 0xffff0000, v121
	v_lshlrev_b32_e32 v126, 16, v122
	v_and_b32_e32 v127, 0xffff0000, v122
	v_lshlrev_b32_e32 v122, 16, v123
	v_and_b32_e32 v123, 0xffff0000, v123
	v_pk_add_f32 v[118:119], v[118:119], v[120:121]
	v_pk_add_f32 v[116:117], v[116:117], v[124:125]
	v_pk_add_f32 v[120:121], v[114:115], v[122:123]
	v_pk_add_f32 v[114:115], v[112:113], v[126:127]
	v_mul_f32_e32 v112, v117, v117
	v_mul_f32_e32 v113, v119, v119
	v_fmac_f32_e32 v112, v116, v116
	v_fmac_f32_e32 v113, v118, v118
	v_add_f32_e32 v112, v112, v113
	v_mul_f32_e32 v113, v115, v115
	v_fmac_f32_e32 v113, v114, v114
	v_add_f32_e32 v112, v113, v112
	v_mul_f32_e32 v113, v121, v121
	v_fmac_f32_e32 v113, v120, v120
	v_add_f32_e32 v112, v113, v112
	v_add_f32_e32 v122, v143, v112
	v_cvt_pk_bf16_f32 v112, v116, v117
	v_cvt_pk_bf16_f32 v113, v118, v119
	v_cvt_pk_bf16_f32 v114, v114, v115
	v_cvt_pk_bf16_f32 v115, v120, v121
	global_store_dwordx4 v[148:149], v[112:115], off offset:256
	s_nop 1
	v_and_b32_e32 v113, 64, v207
	v_xor_b32_e32 v112, 16, v207
	v_add_u32_e32 v113, 64, v113
	v_cmp_lt_i32_e32 vcc, v112, v113
	v_xor_b32_e32 v115, 32, v207
	s_nop 0
	v_cndmask_b32_e32 v112, v207, v112, vcc
	v_lshlrev_b32_e32 v114, 2, v112
	ds_bpermute_b32 v112, v114, v122
	v_cmp_lt_i32_e32 vcc, v115, v113
	s_waitcnt lgkmcnt(0)
	v_add_f32_e32 v112, v122, v112
	v_cndmask_b32_e32 v113, v207, v115, vcc
	v_lshlrev_b32_e32 v115, 2, v113
	ds_bpermute_b32 v113, v115, v112
	s_and_saveexec_b64 s[6:7], s[8:9]
	s_cbranch_execz .LBB0_948
	v_lshlrev_b64 v[116:117], 6, v[130:131]
	v_lshl_add_u64 v[116:117], s[18:19], 0, v[116:117]
	v_lshl_add_u64 v[116:117], s[38:39], 2, v[116:117]
	s_lshl_b32 s42, s28, 2
	s_mov_b32 s43, s36
	v_lshl_add_u64 v[116:117], v[116:117], 0, s[42:43]
	s_waitcnt lgkmcnt(0)
	v_add_f32_e32 v112, v112, v113
	global_store_dword v[116:117], v112, off
; __device__ __forceinline__ unsigned cvt_pk_bf16(float lo, float hi) { unsigned r; asm volatile("v_cvt_pk_bf16_f32 %0, %1, %2" : "=v"(r) : "v"(lo), "v"(hi)); return r; }
; __device__ __forceinline__ void UNPACK8(const u32x4 q, float (&f)[8]) { f[0] = bflo(q.x); f[1] = bfhi(q.x); f[2] = bflo(q.y); f[3] = bfhi(q.y); f[4] = bflo(q.z); f[5] = bfhi(q.z); f[6] = bflo(q.w); f[7] = bfhi(q.w); }
; #define EPI_FOR_ROWS() _Pragma("unroll") for (int ai = 0; ai < 2; ++ai) _Pragma("unroll") for (int m = 0; m < 4; ++m)
;     __device__ __forceinline__ void operator()(const f32x4 (&acc)[2][2][4][2], const Unit& u, int wr, int wc, int fr, int fq) const {
;     ...
;         EPI_FOR_ROWS() {
;             const int row = row0 + ai * 128 + m * 16; float ss = 0.f;
; #pragma unroll
;             for (int bj = 0; bj < 2; ++bj) { const int col = col0 + bj * 128; const size_t off = (size_t)row * 1024 + col;
;                 const u32x4 xw = *(const u32x4*)(xb + off); float xo[8]; UNPACK8(xw, xo);
;                 const f32x4 x0 = (f32x4){xo[0], xo[1], xo[2], xo[3]} + acc[ai][bj][m][0], x1 = (f32x4){xo[4], xo[5], xo[6], xo[7]} + acc[ai][bj][m][1];
;                 ss += (x0[0] * x0[0] + x0[1] * x0[1]) + (x0[2] * x0[2] + x0[3] * x0[3]) + (x1[0] * x1[0] + x1[1] * x1[1]) + (x1[2] * x1[2] + x1[3] * x1[3]);
;                 u32x4 w; w.x = cvt_pk_bf16(x0[0], x0[1]); w.y = cvt_pk_bf16(x0[2], x0[3]); w.z = cvt_pk_bf16(x1[0], x1[1]); w.w = cvt_pk_bf16(x1[2], x1[3]);
;                 *(u32x4*)(xb + off) = w; }
;             ss += __shfl_xor(ss, 16); ss += __shfl_xor(ss, 32);
;             if (fq == 0) ssq[(size_t)row * 16 + u.pn * 4 + wc] = ss;
;         }
.LBB0_948:
	s_or_b64 exec, exec, s[6:7]
	v_or_b32_e32 v112, 16, v130
	s_waitcnt lgkmcnt(0)
	v_ashrrev_i32_e32 v113, 31, v112
	v_lshlrev_b64 v[116:117], 11, v[112:113]
	v_lshl_add_u64 v[116:117], s[22:23], 0, v[116:117]
	v_lshl_add_u64 v[120:121], v[128:129], 1, v[116:117]
	v_mov_b32_e32 v116, v178
	v_mov_b32_e32 v117, v179
	v_mov_b32_e32 v118, v180
	v_mov_b32_e32 v119, v181
	v_lshlrev_b32_e32 v122, 16, v116
	v_and_b32_e32 v123, 0xffff0000, v116
	v_lshlrev_b32_e32 v116, 16, v117
	v_and_b32_e32 v117, 0xffff0000, v117
	v_lshlrev_b32_e32 v124, 16, v118
	v_and_b32_e32 v125, 0xffff0000, v118
	v_lshlrev_b32_e32 v118, 16, v119
	v_and_b32_e32 v119, 0xffff0000, v119
	v_pk_add_f32 v[116:117], v[110:111], v[116:117]
	v_pk_add_f32 v[122:123], v[108:109], v[122:123]
	v_pk_add_f32 v[118:119], v[106:107], v[118:119]
	v_pk_add_f32 v[124:125], v[104:105], v[124:125]
	v_cvt_pk_bf16_f32 v104, v122, v123
	v_cvt_pk_bf16_f32 v105, v116, v117
	v_mul_f32_e32 v123, v123, v123
	v_cvt_pk_bf16_f32 v106, v124, v125
	v_cvt_pk_bf16_f32 v107, v118, v119
	v_mov_b32_e32 v108, v182
	v_mov_b32_e32 v109, v183
	v_mov_b32_e32 v110, v184
	v_mov_b32_e32 v111, v185
	v_mul_f32_e32 v117, v117, v117
	v_mul_f32_e32 v125, v125, v125
	v_fmac_f32_e32 v123, v122, v122
	v_fmac_f32_e32 v117, v116, v116
	v_mul_f32_e32 v119, v119, v119
	v_fmac_f32_e32 v125, v124, v124
	v_add_f32_e32 v116, v123, v117
	v_fmac_f32_e32 v119, v118, v118
	v_add_f32_e32 v116, v125, v116
	v_add_f32_e32 v122, v119, v116
	global_store_dwordx4 v[120:121], v[104:107], off
	v_lshlrev_b32_e32 v116, 16, v108
	v_and_b32_e32 v117, 0xffff0000, v108
	v_lshlrev_b32_e32 v108, 16, v109
	v_and_b32_e32 v109, 0xffff0000, v109
	v_lshlrev_b32_e32 v118, 16, v110
	v_and_b32_e32 v119, 0xffff0000, v110
	v_lshlrev_b32_e32 v110, 16, v111
	v_and_b32_e32 v111, 0xffff0000, v111
	v_pk_add_f32 v[102:103], v[102:103], v[108:109]
	v_pk_add_f32 v[100:101], v[100:101], v[116:117]
	v_pk_add_f32 v[108:109], v[98:99], v[110:111]
	v_pk_add_f32 v[110:111], v[96:97], v[118:119]
	v_mul_f32_e32 v96, v101, v101
	v_mul_f32_e32 v97, v103, v103
	v_mul_f32_e32 v98, v111, v111
	v_fmac_f32_e32 v96, v100, v100
	v_fmac_f32_e32 v97, v102, v102
	v_mul_f32_e32 v99, v109, v109
	v_fmac_f32_e32 v98, v110, v110
	v_add_f32_e32 v96, v96, v97
	v_add_f32_e32 v96, v98, v96
	v_fmac_f32_e32 v99, v108, v108
	v_add_f32_e32 v96, v99, v96
	v_add_f32_e32 v96, v122, v96
	ds_bpermute_b32 v97, v114, v96
	v_cvt_pk_bf16_f32 v98, v100, v101
	v_cvt_pk_bf16_f32 v99, v102, v103
	v_cvt_pk_bf16_f32 v100, v110, v111
	v_cvt_pk_bf16_f32 v101, v108, v109
	s_waitcnt lgkmcnt(0)
	v_add_f32_e32 v96, v96, v97
	ds_bpermute_b32 v97, v115, v96
	global_store_dwordx4 v[120:121], v[98:101], off offset:256
	s_and_saveexec_b64 s[6:7], s[8:9]
	s_cbranch_execz .LBB0_950
	v_lshlrev_b64 v[98:99], 6, v[112:113]
	v_lshl_add_u64 v[98:99], s[18:19], 0, v[98:99]
	v_lshl_add_u64 v[98:99], s[38:39], 2, v[98:99]
	s_lshl_b32 s42, s28, 2
	s_mov_b32 s43, s36
	v_lshl_add_u64 v[98:99], v[98:99], 0, s[42:43]
	s_waitcnt lgkmcnt(0)
	v_add_f32_e32 v96, v96, v97
	global_store_dword v[98:99], v96, off
.LBB0_950:
	s_or_b64 exec, exec, s[6:7]
	v_or_b32_e32 v96, 32, v130
	s_waitcnt lgkmcnt(0)
	v_ashrrev_i32_e32 v97, 31, v96
	v_lshlrev_b64 v[98:99], 11, v[96:97]
	v_lshl_add_u64 v[98:99], s[22:23], 0, v[98:99]
	v_lshl_add_u64 v[102:103], v[128:129], 1, v[98:99]
	v_mov_b32_e32 v98, v186
	v_mov_b32_e32 v99, v187
	v_mov_b32_e32 v100, v188
	v_mov_b32_e32 v101, v189
	v_lshlrev_b32_e32 v104, 16, v98
	v_and_b32_e32 v105, 0xffff0000, v98
	v_lshlrev_b32_e32 v98, 16, v99
	v_and_b32_e32 v99, 0xffff0000, v99
	v_lshlrev_b32_e32 v106, 16, v100
	v_and_b32_e32 v107, 0xffff0000, v100
	v_lshlrev_b32_e32 v100, 16, v101
	v_and_b32_e32 v101, 0xffff0000, v101
	v_pk_add_f32 v[98:99], v[94:95], v[98:99]
	v_pk_add_f32 v[104:105], v[92:93], v[104:105]
	v_pk_add_f32 v[100:101], v[90:91], v[100:101]
	v_pk_add_f32 v[106:107], v[88:89], v[106:107]
	v_cvt_pk_bf16_f32 v88, v104, v105
	v_cvt_pk_bf16_f32 v89, v98, v99
	v_mul_f32_e32 v105, v105, v105
	v_cvt_pk_bf16_f32 v90, v106, v107
	v_cvt_pk_bf16_f32 v91, v100, v101
	v_mov_b32_e32 v92, v190
	v_mov_b32_e32 v93, v191
	v_mov_b32_e32 v94, v192
	v_mov_b32_e32 v95, v193
	v_mul_f32_e32 v99, v99, v99
	v_mul_f32_e32 v107, v107, v107
	v_fmac_f32_e32 v105, v104, v104
	v_fmac_f32_e32 v99, v98, v98
	v_mul_f32_e32 v101, v101, v101
	v_fmac_f32_e32 v107, v106, v106
	v_add_f32_e32 v98, v105, v99
	v_fmac_f32_e32 v101, v100, v100
	v_add_f32_e32 v98, v107, v98
	v_add_f32_e32 v104, v101, v98
	global_store_dwordx4 v[102:103], v[88:91], off
	v_lshlrev_b32_e32 v98, 16, v92
	v_and_b32_e32 v99, 0xffff0000, v92
	v_lshlrev_b32_e32 v92, 16, v93
	v_and_b32_e32 v93, 0xffff0000, v93
	v_lshlrev_b32_e32 v100, 16, v94
	v_and_b32_e32 v101, 0xffff0000, v94
	v_lshlrev_b32_e32 v94, 16, v95
	v_and_b32_e32 v95, 0xffff0000, v95
	v_pk_add_f32 v[86:87], v[86:87], v[92:93]
	v_pk_add_f32 v[84:85], v[84:85], v[98:99]
	v_pk_add_f32 v[92:93], v[82:83], v[94:95]
	v_pk_add_f32 v[94:95], v[80:81], v[100:101]
	v_mul_f32_e32 v80, v85, v85
	v_mul_f32_e32 v81, v87, v87
	v_mul_f32_e32 v82, v95, v95
	v_fmac_f32_e32 v80, v84, v84
	v_fmac_f32_e32 v81, v86, v86
	v_mul_f32_e32 v83, v93, v93
	v_fmac_f32_e32 v82, v94, v94
	v_add_f32_e32 v80, v80, v81
	v_add_f32_e32 v80, v82, v80
	v_fmac_f32_e32 v83, v92, v92
	v_add_f32_e32 v80, v83, v80
	v_add_f32_e32 v80, v104, v80
	ds_bpermute_b32 v81, v114, v80
	v_cvt_pk_bf16_f32 v82, v84, v85
	v_cvt_pk_bf16_f32 v83, v86, v87
	v_cvt_pk_bf16_f32 v84, v94, v95
	v_cvt_pk_bf16_f32 v85, v92, v93
	s_waitcnt lgkmcnt(0)
	v_add_f32_e32 v80, v80, v81
	ds_bpermute_b32 v81, v115, v80
	global_store_dwordx4 v[102:103], v[82:85], off offset:256
	s_and_saveexec_b64 s[6:7], s[8:9]
	s_cbranch_execz .LBB0_952
	v_lshlrev_b64 v[82:83], 6, v[96:97]
	v_lshl_add_u64 v[82:83], s[18:19], 0, v[82:83]
	v_lshl_add_u64 v[82:83], s[38:39], 2, v[82:83]
	s_lshl_b32 s42, s28, 2
	s_mov_b32 s43, s36
	v_lshl_add_u64 v[82:83], v[82:83], 0, s[42:43]
	s_waitcnt lgkmcnt(0)
	v_add_f32_e32 v80, v80, v81
	global_store_dword v[82:83], v80, off
; __device__ __forceinline__ unsigned cvt_pk_bf16(float lo, float hi) { unsigned r; asm volatile("v_cvt_pk_bf16_f32 %0, %1, %2" : "=v"(r) : "v"(lo), "v"(hi)); return r; }
; __device__ __forceinline__ void UNPACK8(const u32x4 q, float (&f)[8]) { f[0] = bflo(q.x); f[1] = bfhi(q.x); f[2] = bflo(q.y); f[3] = bfhi(q.y); f[4] = bflo(q.z); f[5] = bfhi(q.z); f[6] = bflo(q.w); f[7] = bfhi(q.w); }
; #define EPI_FOR_ROWS() _Pragma("unroll") for (int ai = 0; ai < 2; ++ai) _Pragma("unroll") for (int m = 0; m < 4; ++m)
;     __device__ __forceinline__ void operator()(const f32x4 (&acc)[2][2][4][2], const Unit& u, int wr, int wc, int fr, int fq) const {
;     ...
;         EPI_FOR_ROWS() {
;             const int row = row0 + ai * 128 + m * 16; float ss = 0.f;
; #pragma unroll
;             for (int bj = 0; bj < 2; ++bj) { const int col = col0 + bj * 128; const size_t off = (size_t)row * 1024 + col;
;                 const u32x4 xw = *(const u32x4*)(xb + off); float xo[8]; UNPACK8(xw, xo);
;                 const f32x4 x0 = (f32x4){xo[0], xo[1], xo[2], xo[3]} + acc[ai][bj][m][0], x1 = (f32x4){xo[4], xo[5], xo[6], xo[7]} + acc[ai][bj][m][1];
;                 ss += (x0[0] * x0[0] + x0[1] * x0[1]) + (x0[2] * x0[2] + x0[3] * x0[3]) + (x1[0] * x1[0] + x1[1] * x1[1]) + (x1[2] * x1[2] + x1[3] * x1[3]);
;                 u32x4 w; w.x = cvt_pk_bf16(x0[0], x0[1]); w.y = cvt_pk_bf16(x0[2], x0[3]); w.z = cvt_pk_bf16(x1[0], x1[1]); w.w = cvt_pk_bf16(x1[2], x1[3]);
;                 *(u32x4*)(xb + off) = w; }
;             ss += __shfl_xor(ss, 16); ss += __shfl_xor(ss, 32);
;             if (fq == 0) ssq[(size_t)row * 16 + u.pn * 4 + wc] = ss;
;         }
.LBB0_952:
	s_or_b64 exec, exec, s[6:7]
	v_or_b32_e32 v80, 48, v130
	s_waitcnt lgkmcnt(0)
	v_ashrrev_i32_e32 v81, 31, v80
	v_lshlrev_b64 v[82:83], 11, v[80:81]
	v_lshl_add_u64 v[82:83], s[22:23], 0, v[82:83]
	v_lshl_add_u64 v[86:87], v[128:129], 1, v[82:83]
	v_mov_b32_e32 v82, v194
	v_mov_b32_e32 v83, v195
	v_mov_b32_e32 v84, v196
	v_mov_b32_e32 v85, v197
	v_lshlrev_b32_e32 v88, 16, v82
	v_and_b32_e32 v89, 0xffff0000, v82
	v_lshlrev_b32_e32 v82, 16, v83
	v_and_b32_e32 v83, 0xffff0000, v83
	v_lshlrev_b32_e32 v90, 16, v84
	v_and_b32_e32 v91, 0xffff0000, v84
	v_lshlrev_b32_e32 v84, 16, v85
	v_and_b32_e32 v85, 0xffff0000, v85
	v_pk_add_f32 v[82:83], v[78:79], v[82:83]
	v_pk_add_f32 v[88:89], v[76:77], v[88:89]
	v_pk_add_f32 v[84:85], v[74:75], v[84:85]
	v_pk_add_f32 v[90:91], v[72:73], v[90:91]
	v_cvt_pk_bf16_f32 v72, v88, v89
	v_cvt_pk_bf16_f32 v73, v82, v83
	v_mul_f32_e32 v89, v89, v89
	v_cvt_pk_bf16_f32 v74, v90, v91
	v_cvt_pk_bf16_f32 v75, v84, v85
	v_mov_b32_e32 v76, v198
	v_mov_b32_e32 v77, v199
	v_mov_b32_e32 v78, v200
	v_mov_b32_e32 v79, v201
	v_mul_f32_e32 v83, v83, v83
	v_mul_f32_e32 v91, v91, v91
	v_fmac_f32_e32 v89, v88, v88
	v_fmac_f32_e32 v83, v82, v82
	v_mul_f32_e32 v85, v85, v85
	v_fmac_f32_e32 v91, v90, v90
	v_add_f32_e32 v82, v89, v83
	v_fmac_f32_e32 v85, v84, v84
	v_add_f32_e32 v82, v91, v82
	v_add_f32_e32 v88, v85, v82
	global_store_dwordx4 v[86:87], v[72:75], off
	v_lshlrev_b32_e32 v82, 16, v76
	v_and_b32_e32 v83, 0xffff0000, v76
	v_lshlrev_b32_e32 v76, 16, v77
	v_and_b32_e32 v77, 0xffff0000, v77
	v_lshlrev_b32_e32 v84, 16, v78
	v_and_b32_e32 v85, 0xffff0000, v78
	v_lshlrev_b32_e32 v78, 16, v79
	v_and_b32_e32 v79, 0xffff0000, v79
	v_pk_add_f32 v[70:71], v[70:71], v[76:77]
	v_pk_add_f32 v[68:69], v[68:69], v[82:83]
	v_pk_add_f32 v[76:77], v[66:67], v[78:79]
	v_pk_add_f32 v[78:79], v[64:65], v[84:85]
	v_mul_f32_e32 v64, v69, v69
	v_mul_f32_e32 v65, v71, v71
	v_mul_f32_e32 v66, v79, v79
	v_fmac_f32_e32 v64, v68, v68
	v_fmac_f32_e32 v65, v70, v70
	v_mul_f32_e32 v67, v77, v77
	v_fmac_f32_e32 v66, v78, v78
	v_add_f32_e32 v64, v64, v65
	v_add_f32_e32 v64, v66, v64
	v_fmac_f32_e32 v67, v76, v76
	v_add_f32_e32 v64, v67, v64
	v_add_f32_e32 v64, v88, v64
	ds_bpermute_b32 v65, v114, v64
	v_cvt_pk_bf16_f32 v66, v68, v69
	v_cvt_pk_bf16_f32 v67, v70, v71
	v_cvt_pk_bf16_f32 v68, v78, v79
	v_cvt_pk_bf16_f32 v69, v76, v77
	s_waitcnt lgkmcnt(0)
	v_add_f32_e32 v64, v64, v65
	ds_bpermute_b32 v65, v115, v64
	global_store_dwordx4 v[86:87], v[66:69], off offset:256
	s_and_saveexec_b64 s[6:7], s[8:9]
	s_cbranch_execz .LBB0_954
	v_lshlrev_b64 v[66:67], 6, v[80:81]
	v_lshl_add_u64 v[66:67], s[18:19], 0, v[66:67]
	v_lshl_add_u64 v[66:67], s[38:39], 2, v[66:67]
	s_lshl_b32 s42, s28, 2
	s_mov_b32 s43, s36
	v_lshl_add_u64 v[66:67], v[66:67], 0, s[42:43]
	s_waitcnt lgkmcnt(0)
	v_add_f32_e32 v64, v64, v65
	global_store_dword v[66:67], v64, off
.LBB0_954:
	s_or_b64 exec, exec, s[6:7]
	v_add_u32_e32 v64, 0x80, v130
	s_waitcnt lgkmcnt(0)
	v_ashrrev_i32_e32 v65, 31, v64
	v_lshlrev_b64 v[66:67], 11, v[64:65]
	v_lshl_add_u64 v[66:67], s[22:23], 0, v[66:67]
	v_lshl_add_u64 v[70:71], v[128:129], 1, v[66:67]
	v_mov_b32_e32 v66, v202
	v_mov_b32_e32 v67, v203
	v_mov_b32_e32 v68, v204
	v_mov_b32_e32 v69, v205
	v_lshlrev_b32_e32 v72, 16, v66
	v_and_b32_e32 v73, 0xffff0000, v66
	v_lshlrev_b32_e32 v66, 16, v67
	v_and_b32_e32 v67, 0xffff0000, v67
	v_lshlrev_b32_e32 v74, 16, v68
	v_and_b32_e32 v75, 0xffff0000, v68
	v_lshlrev_b32_e32 v68, 16, v69
	v_and_b32_e32 v69, 0xffff0000, v69
	v_pk_add_f32 v[66:67], v[62:63], v[66:67]
	v_pk_add_f32 v[72:73], v[60:61], v[72:73]
	v_pk_add_f32 v[68:69], v[58:59], v[68:69]
	v_pk_add_f32 v[74:75], v[56:57], v[74:75]
	v_cvt_pk_bf16_f32 v56, v72, v73
	v_cvt_pk_bf16_f32 v57, v66, v67
	v_mul_f32_e32 v73, v73, v73
	v_cvt_pk_bf16_f32 v58, v74, v75
	v_cvt_pk_bf16_f32 v59, v68, v69
	v_mov_b32_e32 v60, v214
	v_mov_b32_e32 v61, v215
	v_mov_b32_e32 v62, v216
	v_mov_b32_e32 v63, v217
	v_mul_f32_e32 v67, v67, v67
	v_mul_f32_e32 v75, v75, v75
	v_fmac_f32_e32 v73, v72, v72
	v_fmac_f32_e32 v67, v66, v66
	v_mul_f32_e32 v69, v69, v69
	v_fmac_f32_e32 v75, v74, v74
	v_add_f32_e32 v66, v73, v67
	v_fmac_f32_e32 v69, v68, v68
	v_add_f32_e32 v66, v75, v66
	v_add_f32_e32 v72, v69, v66
	global_store_dwordx4 v[70:71], v[56:59], off
	v_lshlrev_b32_e32 v66, 16, v60
	v_and_b32_e32 v67, 0xffff0000, v60
	v_lshlrev_b32_e32 v60, 16, v61
	v_and_b32_e32 v61, 0xffff0000, v61
	v_lshlrev_b32_e32 v68, 16, v62
	v_and_b32_e32 v69, 0xffff0000, v62
	v_lshlrev_b32_e32 v62, 16, v63
	v_and_b32_e32 v63, 0xffff0000, v63
	v_pk_add_f32 v[54:55], v[54:55], v[60:61]
	v_pk_add_f32 v[52:53], v[52:53], v[66:67]
	v_pk_add_f32 v[60:61], v[50:51], v[62:63]
	v_pk_add_f32 v[62:63], v[48:49], v[68:69]
	v_mul_f32_e32 v48, v53, v53
	v_mul_f32_e32 v49, v55, v55
	v_mul_f32_e32 v50, v63, v63
	v_fmac_f32_e32 v48, v52, v52
	v_fmac_f32_e32 v49, v54, v54
	v_mul_f32_e32 v51, v61, v61
	v_fmac_f32_e32 v50, v62, v62
	v_add_f32_e32 v48, v48, v49
	v_add_f32_e32 v48, v50, v48
	v_fmac_f32_e32 v51, v60, v60
	v_add_f32_e32 v48, v51, v48
	v_add_f32_e32 v48, v72, v48
	ds_bpermute_b32 v49, v114, v48
	v_cvt_pk_bf16_f32 v50, v52, v53
	v_cvt_pk_bf16_f32 v51, v54, v55
	v_cvt_pk_bf16_f32 v52, v62, v63
	v_cvt_pk_bf16_f32 v53, v60, v61
	s_waitcnt lgkmcnt(0)
	v_add_f32_e32 v48, v48, v49
	ds_bpermute_b32 v49, v115, v48
	global_store_dwordx4 v[70:71], v[50:53], off offset:256
	s_and_saveexec_b64 s[6:7], s[8:9]
	s_cbranch_execz .LBB0_956
	v_lshlrev_b64 v[50:51], 6, v[64:65]
	v_lshl_add_u64 v[50:51], s[18:19], 0, v[50:51]
	v_lshl_add_u64 v[50:51], s[38:39], 2, v[50:51]
	s_lshl_b32 s42, s28, 2
	s_mov_b32 s43, s36
	v_lshl_add_u64 v[50:51], v[50:51], 0, s[42:43]
	s_waitcnt lgkmcnt(0)
	v_add_f32_e32 v48, v48, v49
	global_store_dword v[50:51], v48, off
; __device__ __forceinline__ unsigned cvt_pk_bf16(float lo, float hi) { unsigned r; asm volatile("v_cvt_pk_bf16_f32 %0, %1, %2" : "=v"(r) : "v"(lo), "v"(hi)); return r; }
; __device__ __forceinline__ void UNPACK8(const u32x4 q, float (&f)[8]) { f[0] = bflo(q.x); f[1] = bfhi(q.x); f[2] = bflo(q.y); f[3] = bfhi(q.y); f[4] = bflo(q.z); f[5] = bfhi(q.z); f[6] = bflo(q.w); f[7] = bfhi(q.w); }
; #define EPI_FOR_ROWS() _Pragma("unroll") for (int ai = 0; ai < 2; ++ai) _Pragma("unroll") for (int m = 0; m < 4; ++m)
;     __device__ __forceinline__ void operator()(const f32x4 (&acc)[2][2][4][2], const Unit& u, int wr, int wc, int fr, int fq) const {
;     ...
;         EPI_FOR_ROWS() {
;             const int row = row0 + ai * 128 + m * 16; float ss = 0.f;
; #pragma unroll
;             for (int bj = 0; bj < 2; ++bj) { const int col = col0 + bj * 128; const size_t off = (size_t)row * 1024 + col;
;                 const u32x4 xw = *(const u32x4*)(xb + off); float xo[8]; UNPACK8(xw, xo);
;                 const f32x4 x0 = (f32x4){xo[0], xo[1], xo[2], xo[3]} + acc[ai][bj][m][0], x1 = (f32x4){xo[4], xo[5], xo[6], xo[7]} + acc[ai][bj][m][1];
;                 ss += (x0[0] * x0[0] + x0[1] * x0[1]) + (x0[2] * x0[2] + x0[3] * x0[3]) + (x1[0] * x1[0] + x1[1] * x1[1]) + (x1[2] * x1[2] + x1[3] * x1[3]);
;                 u32x4 w; w.x = cvt_pk_bf16(x0[0], x0[1]); w.y = cvt_pk_bf16(x0[2], x0[3]); w.z = cvt_pk_bf16(x1[0], x1[1]); w.w = cvt_pk_bf16(x1[2], x1[3]);
;                 *(u32x4*)(xb + off) = w; }
;             ss += __shfl_xor(ss, 16); ss += __shfl_xor(ss, 32);
;             if (fq == 0) ssq[(size_t)row * 16 + u.pn * 4 + wc] = ss;
;         }
.LBB0_956:
	s_or_b64 exec, exec, s[6:7]
	v_add_u32_e32 v48, 0x90, v130
	s_waitcnt lgkmcnt(0)
	v_ashrrev_i32_e32 v49, 31, v48
	v_lshlrev_b64 v[50:51], 11, v[48:49]
	v_lshl_add_u64 v[50:51], s[22:23], 0, v[50:51]
	v_lshl_add_u64 v[54:55], v[128:129], 1, v[50:51]
	v_mov_b32_e32 v50, v218
	v_mov_b32_e32 v51, v219
	v_mov_b32_e32 v52, v220
	v_mov_b32_e32 v53, v221
	v_lshlrev_b32_e32 v56, 16, v50
	v_and_b32_e32 v57, 0xffff0000, v50
	v_lshlrev_b32_e32 v50, 16, v51
	v_and_b32_e32 v51, 0xffff0000, v51
	v_lshlrev_b32_e32 v58, 16, v52
	v_and_b32_e32 v59, 0xffff0000, v52
	v_lshlrev_b32_e32 v52, 16, v53
	v_and_b32_e32 v53, 0xffff0000, v53
	v_pk_add_f32 v[50:51], v[46:47], v[50:51]
	v_pk_add_f32 v[56:57], v[44:45], v[56:57]
	v_pk_add_f32 v[52:53], v[42:43], v[52:53]
	v_pk_add_f32 v[58:59], v[40:41], v[58:59]
	v_cvt_pk_bf16_f32 v40, v56, v57
	v_cvt_pk_bf16_f32 v41, v50, v51
	v_mul_f32_e32 v57, v57, v57
	v_cvt_pk_bf16_f32 v42, v58, v59
	v_cvt_pk_bf16_f32 v43, v52, v53
	v_mov_b32_e32 v44, v222
	v_mov_b32_e32 v45, v223
	v_mov_b32_e32 v46, v224
	v_mov_b32_e32 v47, v225
	v_mul_f32_e32 v51, v51, v51
	v_mul_f32_e32 v59, v59, v59
	v_fmac_f32_e32 v57, v56, v56
	v_fmac_f32_e32 v51, v50, v50
	v_mul_f32_e32 v53, v53, v53
	v_fmac_f32_e32 v59, v58, v58
	v_add_f32_e32 v50, v57, v51
	v_fmac_f32_e32 v53, v52, v52
	v_add_f32_e32 v50, v59, v50
	v_add_f32_e32 v56, v53, v50
	global_store_dwordx4 v[54:55], v[40:43], off
	v_lshlrev_b32_e32 v50, 16, v44
	v_and_b32_e32 v51, 0xffff0000, v44
	v_lshlrev_b32_e32 v44, 16, v45
	v_and_b32_e32 v45, 0xffff0000, v45
	v_lshlrev_b32_e32 v52, 16, v46
	v_and_b32_e32 v53, 0xffff0000, v46
	v_lshlrev_b32_e32 v46, 16, v47
	v_and_b32_e32 v47, 0xffff0000, v47
	v_pk_add_f32 v[38:39], v[38:39], v[44:45]
	v_pk_add_f32 v[36:37], v[36:37], v[50:51]
	v_pk_add_f32 v[44:45], v[34:35], v[46:47]
	v_pk_add_f32 v[46:47], v[32:33], v[52:53]
	v_mul_f32_e32 v32, v37, v37
	v_mul_f32_e32 v33, v39, v39
	v_mul_f32_e32 v34, v47, v47
	v_fmac_f32_e32 v32, v36, v36
	v_fmac_f32_e32 v33, v38, v38
	v_mul_f32_e32 v35, v45, v45
	v_fmac_f32_e32 v34, v46, v46
	v_add_f32_e32 v32, v32, v33
	v_add_f32_e32 v32, v34, v32
	v_fmac_f32_e32 v35, v44, v44
	v_add_f32_e32 v32, v35, v32
	v_add_f32_e32 v32, v56, v32
	ds_bpermute_b32 v33, v114, v32
	v_cvt_pk_bf16_f32 v34, v36, v37
	v_cvt_pk_bf16_f32 v35, v38, v39
	v_cvt_pk_bf16_f32 v36, v46, v47
	v_cvt_pk_bf16_f32 v37, v44, v45
	s_waitcnt lgkmcnt(0)
	v_add_f32_e32 v32, v32, v33
	ds_bpermute_b32 v33, v115, v32
	global_store_dwordx4 v[54:55], v[34:37], off offset:256
	s_and_saveexec_b64 s[6:7], s[8:9]
	s_cbranch_execz .LBB0_958
	v_lshlrev_b64 v[34:35], 6, v[48:49]
	v_lshl_add_u64 v[34:35], s[18:19], 0, v[34:35]
	v_lshl_add_u64 v[34:35], s[38:39], 2, v[34:35]
	s_lshl_b32 s42, s28, 2
	s_mov_b32 s43, s36
	v_lshl_add_u64 v[34:35], v[34:35], 0, s[42:43]
	s_waitcnt lgkmcnt(0)
	v_add_f32_e32 v32, v32, v33
	global_store_dword v[34:35], v32, off
; __device__ __forceinline__ unsigned cvt_pk_bf16(float lo, float hi) { unsigned r; asm volatile("v_cvt_pk_bf16_f32 %0, %1, %2" : "=v"(r) : "v"(lo), "v"(hi)); return r; }
; __device__ __forceinline__ void UNPACK8(const u32x4 q, float (&f)[8]) { f[0] = bflo(q.x); f[1] = bfhi(q.x); f[2] = bflo(q.y); f[3] = bfhi(q.y); f[4] = bflo(q.z); f[5] = bfhi(q.z); f[6] = bflo(q.w); f[7] = bfhi(q.w); }
; #define EPI_FOR_ROWS() _Pragma("unroll") for (int ai = 0; ai < 2; ++ai) _Pragma("unroll") for (int m = 0; m < 4; ++m)
;     __device__ __forceinline__ void operator()(const f32x4 (&acc)[2][2][4][2], const Unit& u, int wr, int wc, int fr, int fq) const {
;     ...
;         EPI_FOR_ROWS() {
;             const int row = row0 + ai * 128 + m * 16; float ss = 0.f;
; #pragma unroll
;             for (int bj = 0; bj < 2; ++bj) { const int col = col0 + bj * 128; const size_t off = (size_t)row * 1024 + col;
;                 const u32x4 xw = *(const u32x4*)(xb + off); float xo[8]; UNPACK8(xw, xo);
;                 const f32x4 x0 = (f32x4){xo[0], xo[1], xo[2], xo[3]} + acc[ai][bj][m][0], x1 = (f32x4){xo[4], xo[5], xo[6], xo[7]} + acc[ai][bj][m][1];
;                 ss += (x0[0] * x0[0] + x0[1] * x0[1]) + (x0[2] * x0[2] + x0[3] * x0[3]) + (x1[0] * x1[0] + x1[1] * x1[1]) + (x1[2] * x1[2] + x1[3] * x1[3]);
;                 u32x4 w; w.x = cvt_pk_bf16(x0[0], x0[1]); w.y = cvt_pk_bf16(x0[2], x0[3]); w.z = cvt_pk_bf16(x1[0], x1[1]); w.w = cvt_pk_bf16(x1[2], x1[3]);
;                 *(u32x4*)(xb + off) = w; }
;             ss += __shfl_xor(ss, 16); ss += __shfl_xor(ss, 32);
;             if (fq == 0) ssq[(size_t)row * 16 + u.pn * 4 + wc] = ss;
;         }
.LBB0_958:
	s_or_b64 exec, exec, s[6:7]
	v_add_u32_e32 v32, 0xa0, v130
	s_waitcnt lgkmcnt(0)
	v_ashrrev_i32_e32 v33, 31, v32
	v_lshlrev_b64 v[34:35], 11, v[32:33]
	v_lshl_add_u64 v[34:35], s[22:23], 0, v[34:35]
	v_lshl_add_u64 v[38:39], v[128:129], 1, v[34:35]
	v_mov_b32_e32 v34, v226
	v_mov_b32_e32 v35, v227
	v_mov_b32_e32 v36, v228
	v_mov_b32_e32 v37, v229
	v_lshlrev_b32_e32 v40, 16, v34
	v_and_b32_e32 v41, 0xffff0000, v34
	v_lshlrev_b32_e32 v34, 16, v35
	v_and_b32_e32 v35, 0xffff0000, v35
	v_lshlrev_b32_e32 v42, 16, v36
	v_and_b32_e32 v43, 0xffff0000, v36
	v_lshlrev_b32_e32 v36, 16, v37
	v_and_b32_e32 v37, 0xffff0000, v37
	v_pk_add_f32 v[34:35], v[30:31], v[34:35]
	v_pk_add_f32 v[40:41], v[28:29], v[40:41]
	v_pk_add_f32 v[36:37], v[26:27], v[36:37]
	v_pk_add_f32 v[42:43], v[24:25], v[42:43]
	v_cvt_pk_bf16_f32 v24, v40, v41
	v_cvt_pk_bf16_f32 v25, v34, v35
	v_mul_f32_e32 v41, v41, v41
	v_cvt_pk_bf16_f32 v26, v42, v43
	v_cvt_pk_bf16_f32 v27, v36, v37
	v_mov_b32_e32 v28, v230
	v_mov_b32_e32 v29, v231
	v_mov_b32_e32 v30, v232
	v_mov_b32_e32 v31, v233
	v_mul_f32_e32 v35, v35, v35
	v_mul_f32_e32 v43, v43, v43
	v_fmac_f32_e32 v41, v40, v40
	v_fmac_f32_e32 v35, v34, v34
	v_mul_f32_e32 v37, v37, v37
	v_fmac_f32_e32 v43, v42, v42
	v_add_f32_e32 v34, v41, v35
	v_fmac_f32_e32 v37, v36, v36
	v_add_f32_e32 v34, v43, v34
	v_add_f32_e32 v40, v37, v34
	global_store_dwordx4 v[38:39], v[24:27], off
	v_lshlrev_b32_e32 v34, 16, v28
	v_and_b32_e32 v35, 0xffff0000, v28
	v_lshlrev_b32_e32 v28, 16, v29
	v_and_b32_e32 v29, 0xffff0000, v29
	v_lshlrev_b32_e32 v36, 16, v30
	v_and_b32_e32 v37, 0xffff0000, v30
	v_lshlrev_b32_e32 v30, 16, v31
	v_and_b32_e32 v31, 0xffff0000, v31
	v_pk_add_f32 v[22:23], v[22:23], v[28:29]
	v_pk_add_f32 v[20:21], v[20:21], v[34:35]
	v_pk_add_f32 v[28:29], v[18:19], v[30:31]
	v_pk_add_f32 v[30:31], v[16:17], v[36:37]
	v_mul_f32_e32 v16, v21, v21
	v_mul_f32_e32 v17, v23, v23
	v_mul_f32_e32 v18, v31, v31
	v_fmac_f32_e32 v16, v20, v20
	v_fmac_f32_e32 v17, v22, v22
	v_mul_f32_e32 v19, v29, v29
	v_fmac_f32_e32 v18, v30, v30
	v_add_f32_e32 v16, v16, v17
	v_add_f32_e32 v16, v18, v16
	v_fmac_f32_e32 v19, v28, v28
	v_add_f32_e32 v16, v19, v16
	v_add_f32_e32 v16, v40, v16
	ds_bpermute_b32 v17, v114, v16
	v_cvt_pk_bf16_f32 v18, v20, v21
	v_cvt_pk_bf16_f32 v19, v22, v23
	v_cvt_pk_bf16_f32 v20, v30, v31
	v_cvt_pk_bf16_f32 v21, v28, v29
	s_waitcnt lgkmcnt(0)
	v_add_f32_e32 v16, v16, v17
	ds_bpermute_b32 v17, v115, v16
	global_store_dwordx4 v[38:39], v[18:21], off offset:256
	s_and_saveexec_b64 s[6:7], s[8:9]
	s_cbranch_execz .LBB0_960
	v_lshlrev_b64 v[18:19], 6, v[32:33]
	v_lshl_add_u64 v[18:19], s[18:19], 0, v[18:19]
	v_lshl_add_u64 v[18:19], s[38:39], 2, v[18:19]
	s_lshl_b32 s42, s28, 2
	s_mov_b32 s43, s36
	v_lshl_add_u64 v[18:19], v[18:19], 0, s[42:43]
	s_waitcnt lgkmcnt(0)
	v_add_f32_e32 v16, v16, v17
	global_store_dword v[18:19], v16, off
.LBB0_960:
	s_or_b64 exec, exec, s[6:7]
	v_add_u32_e32 v16, 0xb0, v130
	s_waitcnt lgkmcnt(0)
	v_ashrrev_i32_e32 v17, 31, v16
	v_lshlrev_b64 v[18:19], 11, v[16:17]
	v_lshl_add_u64 v[18:19], s[22:23], 0, v[18:19]
	v_lshl_add_u64 v[22:23], v[128:129], 1, v[18:19]
	v_mov_b32_e32 v18, v234
	v_mov_b32_e32 v19, v235
	v_mov_b32_e32 v20, v236
	v_mov_b32_e32 v21, v237
	v_lshlrev_b32_e32 v24, 16, v18
	v_and_b32_e32 v25, 0xffff0000, v18
	v_lshlrev_b32_e32 v18, 16, v19
	v_and_b32_e32 v19, 0xffff0000, v19
	v_lshlrev_b32_e32 v26, 16, v20
	v_and_b32_e32 v27, 0xffff0000, v20
	v_lshlrev_b32_e32 v20, 16, v21
	v_and_b32_e32 v21, 0xffff0000, v21
	v_pk_add_f32 v[18:19], v[14:15], v[18:19]
	v_pk_add_f32 v[24:25], v[12:13], v[24:25]
	v_pk_add_f32 v[20:21], v[10:11], v[20:21]
	v_pk_add_f32 v[26:27], v[8:9], v[26:27]
	v_cvt_pk_bf16_f32 v8, v24, v25
	v_cvt_pk_bf16_f32 v9, v18, v19
	v_mul_f32_e32 v25, v25, v25
	v_cvt_pk_bf16_f32 v10, v26, v27
	v_cvt_pk_bf16_f32 v11, v20, v21
	v_mov_b32_e32 v12, v238
	v_mov_b32_e32 v13, v239
	v_mov_b32_e32 v14, v240
	v_mov_b32_e32 v15, v241
	v_mul_f32_e32 v19, v19, v19
	v_mul_f32_e32 v27, v27, v27
	v_fmac_f32_e32 v25, v24, v24
	v_fmac_f32_e32 v19, v18, v18
	v_mul_f32_e32 v21, v21, v21
	v_fmac_f32_e32 v27, v26, v26
	v_add_f32_e32 v18, v25, v19
	v_fmac_f32_e32 v21, v20, v20
	v_add_f32_e32 v18, v27, v18
	v_add_f32_e32 v24, v21, v18
	global_store_dwordx4 v[22:23], v[8:11], off
	v_lshlrev_b32_e32 v18, 16, v12
	v_and_b32_e32 v19, 0xffff0000, v12
	v_lshlrev_b32_e32 v12, 16, v13
	v_and_b32_e32 v13, 0xffff0000, v13
	v_lshlrev_b32_e32 v20, 16, v14
	v_and_b32_e32 v21, 0xffff0000, v14
	v_lshlrev_b32_e32 v14, 16, v15
	v_and_b32_e32 v15, 0xffff0000, v15
	v_pk_add_f32 v[6:7], v[6:7], v[12:13]
	v_pk_add_f32 v[4:5], v[4:5], v[18:19]
	v_pk_add_f32 v[12:13], v[2:3], v[14:15]
	v_pk_add_f32 v[14:15], v[0:1], v[20:21]
	v_mul_f32_e32 v0, v5, v5
	v_mul_f32_e32 v1, v7, v7
	v_mul_f32_e32 v2, v15, v15
	v_fmac_f32_e32 v0, v4, v4
	v_fmac_f32_e32 v1, v6, v6
	v_mul_f32_e32 v3, v13, v13
	v_fmac_f32_e32 v2, v14, v14
	v_add_f32_e32 v0, v0, v1
	v_add_f32_e32 v0, v2, v0
	v_fmac_f32_e32 v3, v12, v12
	v_add_f32_e32 v0, v3, v0
	v_add_f32_e32 v0, v24, v0
	ds_bpermute_b32 v1, v114, v0
	v_cvt_pk_bf16_f32 v2, v4, v5
	v_cvt_pk_bf16_f32 v3, v6, v7
	v_cvt_pk_bf16_f32 v4, v14, v15
	v_cvt_pk_bf16_f32 v5, v12, v13
	s_waitcnt lgkmcnt(0)
	v_add_f32_e32 v0, v0, v1
	ds_bpermute_b32 v1, v115, v0
	global_store_dwordx4 v[22:23], v[2:5], off offset:256
	s_and_saveexec_b64 s[6:7], s[8:9]
	s_cbranch_execz .LBB0_962
	v_lshlrev_b64 v[2:3], 6, v[16:17]
	v_lshl_add_u64 v[2:3], s[18:19], 0, v[2:3]
	v_lshl_add_u64 v[2:3], s[38:39], 2, v[2:3]
	s_lshl_b32 s38, s28, 2
	s_mov_b32 s39, s36
	v_lshl_add_u64 v[2:3], v[2:3], 0, s[38:39]
	s_waitcnt lgkmcnt(0)
	v_add_f32_e32 v0, v0, v1
	global_store_dword v[2:3], v0, off

; __device__ __forceinline__ unsigned cvt_pk_bf16(float lo, float hi) { unsigned r; asm volatile("v_cvt_pk_bf16_f32 %0, %1, %2" : "=v"(r) : "v"(lo), "v"(hi)); return r; }
; __device__ __forceinline__ void UNPACK8(const u32x4 q, float (&f)[8]) { f[0] = bflo(q.x); f[1] = bfhi(q.x); f[2] = bflo(q.y); f[3] = bfhi(q.y); f[4] = bflo(q.z); f[5] = bfhi(q.z); f[6] = bflo(q.w); f[7] = bfhi(q.w); }
; #define EPI_FOR_ROWS() _Pragma("unroll") for (int ai = 0; ai < 2; ++ai) _Pragma("unroll") for (int m = 0; m < 4; ++m)
;     __device__ __forceinline__ void operator()(const f32x4 (&acc)[2][2][4][2], const Unit& u, int wr, int wc, int fr, int fq) const {
;     ...
;         EPI_FOR_ROWS() {
;             const int row = row0 + ai * 128 + m * 16; float ss = 0.f;
; #pragma unroll
;             for (int bj = 0; bj < 2; ++bj) { const int col = col0 + bj * 128; const size_t off = (size_t)row * 1024 + col;
;                 const u32x4 xw = *(const u32x4*)(xb + off); float xo[8]; UNPACK8(xw, xo);
;                 const f32x4 x0 = (f32x4){xo[0], xo[1], xo[2], xo[3]} + acc[ai][bj][m][0], x1 = (f32x4){xo[4], xo[5], xo[6], xo[7]} + acc[ai][bj][m][1];
;                 ss += (x0[0] * x0[0] + x0[1] * x0[1]) + (x0[2] * x0[2] + x0[3] * x0[3]) + (x1[0] * x1[0] + x1[1] * x1[1]) + (x1[2] * x1[2] + x1[3] * x1[3]);
;                 u32x4 w; w.x = cvt_pk_bf16(x0[0], x0[1]); w.y = cvt_pk_bf16(x0[2], x0[3]); w.z = cvt_pk_bf16(x1[0], x1[1]); w.w = cvt_pk_bf16(x1[2], x1[3]);
;                 *(u32x4*)(xb + off) = w; }
;             ss += __shfl_xor(ss, 16); ss += __shfl_xor(ss, 32);
;             if (fq == 0) ssq[(size_t)row * 16 + u.pn * 4 + wc] = ss;
;         }
.LBB0_1143:
	v_lshl_add_u32 v130, s67, 8, v136
	v_ashrrev_i32_e32 v131, 31, v130
	v_lshl_or_b32 v128, s66, 8, v137
	v_lshlrev_b64 v[144:145], 11, v[130:131]
	v_ashrrev_i32_e32 v129, 31, v128
	v_lshl_add_u64 v[144:145], s[22:23], 0, v[144:145]
	v_lshl_add_u64 v[148:149], v[128:129], 1, v[144:145]
	global_load_dwordx4 v[156:159], v[148:149], off
	global_load_dwordx4 v[166:169], v[148:149], off offset:256
	s_mov_b32 s12, 0x8000
	s_mov_b32 s13, 0
	v_lshl_add_u64 v[182:183], v[148:149], 0, s[12:13]
	global_load_dwordx4 v[178:181], v[182:183], off
	global_load_dwordx4 v[182:185], v[182:183], off offset:256
	s_mov_b32 s12, 0x10000
	s_mov_b32 s13, 0
	v_lshl_add_u64 v[190:191], v[148:149], 0, s[12:13]
	global_load_dwordx4 v[186:189], v[190:191], off
	global_load_dwordx4 v[190:193], v[190:191], off offset:256
	s_mov_b32 s12, 0x18000
	s_mov_b32 s13, 0
	v_lshl_add_u64 v[198:199], v[148:149], 0, s[12:13]
	global_load_dwordx4 v[194:197], v[198:199], off
	global_load_dwordx4 v[198:201], v[198:199], off offset:256
	s_mov_b32 s12, 0x40000
	s_mov_b32 s13, 0
	v_lshl_add_u64 v[214:215], v[148:149], 0, s[12:13]
	global_load_dwordx4 v[202:205], v[214:215], off
	global_load_dwordx4 v[214:217], v[214:215], off offset:256
	s_mov_b32 s12, 0x48000
	s_mov_b32 s13, 0
	v_lshl_add_u64 v[222:223], v[148:149], 0, s[12:13]
	global_load_dwordx4 v[218:221], v[222:223], off
	global_load_dwordx4 v[222:225], v[222:223], off offset:256
	s_mov_b32 s12, 0x50000
	s_mov_b32 s13, 0
	v_lshl_add_u64 v[230:231], v[148:149], 0, s[12:13]
	global_load_dwordx4 v[226:229], v[230:231], off
	global_load_dwordx4 v[230:233], v[230:231], off offset:256
	s_mov_b32 s12, 0x58000
	s_mov_b32 s13, 0
	v_lshl_add_u64 v[238:239], v[148:149], 0, s[12:13]
	global_load_dwordx4 v[234:237], v[238:239], off
	global_load_dwordx4 v[238:241], v[238:239], off offset:256
	s_waitcnt vmcnt(0)
	v_mov_b32_e32 v144, v156
	v_mov_b32_e32 v145, v157
	v_mov_b32_e32 v146, v158
	v_mov_b32_e32 v147, v159
	s_lshl_b32 s12, s66, 2
	s_ashr_i32 s13, s12, 31
	v_lshlrev_b32_e32 v150, 16, v144
	v_and_b32_e32 v151, 0xffff0000, v144
	v_lshlrev_b32_e32 v144, 16, v145
	v_and_b32_e32 v145, 0xffff0000, v145
	v_lshlrev_b32_e32 v152, 16, v146
	v_and_b32_e32 v153, 0xffff0000, v146
	v_lshlrev_b32_e32 v146, 16, v147
	v_and_b32_e32 v147, 0xffff0000, v147
	v_pk_add_f32 v[126:127], v[126:127], v[144:145]
	v_pk_add_f32 v[124:125], v[124:125], v[150:151]
	v_pk_add_f32 v[144:145], v[122:123], v[146:147]
	v_pk_add_f32 v[122:123], v[120:121], v[152:153]
	v_mul_f32_e32 v120, v125, v125
	v_mul_f32_e32 v121, v127, v127
	v_fmac_f32_e32 v120, v124, v124
	v_fmac_f32_e32 v121, v126, v126
	v_add_f32_e32 v120, v120, v121
	v_mul_f32_e32 v121, v123, v123
	v_fmac_f32_e32 v121, v122, v122
	v_add_f32_e32 v120, v121, v120
	v_mul_f32_e32 v121, v145, v145
	v_fmac_f32_e32 v121, v144, v144
	v_add_f32_e32 v143, v121, v120
	v_cvt_pk_bf16_f32 v120, v124, v125
	v_cvt_pk_bf16_f32 v121, v126, v127
	v_cvt_pk_bf16_f32 v122, v122, v123
	v_cvt_pk_bf16_f32 v123, v144, v145
	global_store_dwordx4 v[148:149], v[120:123], off
	s_nop 1
	v_mov_b32_e32 v120, v166
	v_mov_b32_e32 v121, v167
	v_mov_b32_e32 v122, v168
	v_mov_b32_e32 v123, v169
	v_lshlrev_b32_e32 v124, 16, v120
	v_and_b32_e32 v125, 0xffff0000, v120
	v_lshlrev_b32_e32 v120, 16, v121
	v_and_b32_e32 v121, 0xffff0000, v121
	v_lshlrev_b32_e32 v126, 16, v122
	v_and_b32_e32 v127, 0xffff0000, v122
	v_lshlrev_b32_e32 v122, 16, v123
	v_and_b32_e32 v123, 0xffff0000, v123
	v_pk_add_f32 v[118:119], v[118:119], v[120:121]
	v_pk_add_f32 v[116:117], v[116:117], v[124:125]
	v_pk_add_f32 v[120:121], v[114:115], v[122:123]
	v_pk_add_f32 v[114:115], v[112:113], v[126:127]
	v_mul_f32_e32 v112, v117, v117
	v_mul_f32_e32 v113, v119, v119
	v_fmac_f32_e32 v112, v116, v116
	v_fmac_f32_e32 v113, v118, v118
	v_add_f32_e32 v112, v112, v113
	v_mul_f32_e32 v113, v115, v115
	v_fmac_f32_e32 v113, v114, v114
	v_add_f32_e32 v112, v113, v112
	v_mul_f32_e32 v113, v121, v121
	v_fmac_f32_e32 v113, v120, v120
	v_add_f32_e32 v112, v113, v112
	v_add_f32_e32 v122, v143, v112
	v_cvt_pk_bf16_f32 v112, v116, v117
	v_cvt_pk_bf16_f32 v113, v118, v119
	v_cvt_pk_bf16_f32 v114, v114, v115
	v_cvt_pk_bf16_f32 v115, v120, v121
	global_store_dwordx4 v[148:149], v[112:115], off offset:256
	s_nop 1
	v_and_b32_e32 v113, 64, v207
	v_xor_b32_e32 v112, 16, v207
	v_add_u32_e32 v113, 64, v113
	v_cmp_lt_i32_e32 vcc, v112, v113
	v_xor_b32_e32 v115, 32, v207
	s_nop 0
	v_cndmask_b32_e32 v112, v207, v112, vcc
	v_lshlrev_b32_e32 v114, 2, v112
	ds_bpermute_b32 v112, v114, v122
	v_cmp_lt_i32_e32 vcc, v115, v113
	s_waitcnt lgkmcnt(0)
	v_add_f32_e32 v112, v122, v112
	v_cndmask_b32_e32 v113, v207, v115, vcc
	v_lshlrev_b32_e32 v115, 2, v113
	ds_bpermute_b32 v113, v115, v112
	s_and_saveexec_b64 s[14:15], s[6:7]
	s_cbranch_execz .LBB0_1145
	v_lshlrev_b64 v[116:117], 6, v[130:131]
	v_lshl_add_u64 v[116:117], s[20:21], 0, v[116:117]
	v_lshl_add_u64 v[116:117], s[12:13], 2, v[116:117]
	s_lshl_b32 s16, s28, 2
	s_mov_b32 s17, s36
	v_lshl_add_u64 v[116:117], v[116:117], 0, s[16:17]
	s_waitcnt lgkmcnt(0)
	v_add_f32_e32 v112, v112, v113
	global_store_dword v[116:117], v112, off
; __device__ __forceinline__ unsigned cvt_pk_bf16(float lo, float hi) { unsigned r; asm volatile("v_cvt_pk_bf16_f32 %0, %1, %2" : "=v"(r) : "v"(lo), "v"(hi)); return r; }
; __device__ __forceinline__ void UNPACK8(const u32x4 q, float (&f)[8]) { f[0] = bflo(q.x); f[1] = bfhi(q.x); f[2] = bflo(q.y); f[3] = bfhi(q.y); f[4] = bflo(q.z); f[5] = bfhi(q.z); f[6] = bflo(q.w); f[7] = bfhi(q.w); }
; #define EPI_FOR_ROWS() _Pragma("unroll") for (int ai = 0; ai < 2; ++ai) _Pragma("unroll") for (int m = 0; m < 4; ++m)
;     __device__ __forceinline__ void operator()(const f32x4 (&acc)[2][2][4][2], const Unit& u, int wr, int wc, int fr, int fq) const {
;     ...
;         EPI_FOR_ROWS() {
;             const int row = row0 + ai * 128 + m * 16; float ss = 0.f;
; #pragma unroll
;             for (int bj = 0; bj < 2; ++bj) { const int col = col0 + bj * 128; const size_t off = (size_t)row * 1024 + col;
;                 const u32x4 xw = *(const u32x4*)(xb + off); float xo[8]; UNPACK8(xw, xo);
;                 const f32x4 x0 = (f32x4){xo[0], xo[1], xo[2], xo[3]} + acc[ai][bj][m][0], x1 = (f32x4){xo[4], xo[5], xo[6], xo[7]} + acc[ai][bj][m][1];
;                 ss += (x0[0] * x0[0] + x0[1] * x0[1]) + (x0[2] * x0[2] + x0[3] * x0[3]) + (x1[0] * x1[0] + x1[1] * x1[1]) + (x1[2] * x1[2] + x1[3] * x1[3]);
;                 u32x4 w; w.x = cvt_pk_bf16(x0[0], x0[1]); w.y = cvt_pk_bf16(x0[2], x0[3]); w.z = cvt_pk_bf16(x1[0], x1[1]); w.w = cvt_pk_bf16(x1[2], x1[3]);
;                 *(u32x4*)(xb + off) = w; }
;             ss += __shfl_xor(ss, 16); ss += __shfl_xor(ss, 32);
;             if (fq == 0) ssq[(size_t)row * 16 + u.pn * 4 + wc] = ss;
;         }
.LBB0_1145:
	s_or_b64 exec, exec, s[14:15]
	v_or_b32_e32 v112, 16, v130
	s_waitcnt lgkmcnt(0)
	v_ashrrev_i32_e32 v113, 31, v112
	v_lshlrev_b64 v[116:117], 11, v[112:113]
	v_lshl_add_u64 v[116:117], s[22:23], 0, v[116:117]
	v_lshl_add_u64 v[120:121], v[128:129], 1, v[116:117]
	v_mov_b32_e32 v116, v178
	v_mov_b32_e32 v117, v179
	v_mov_b32_e32 v118, v180
	v_mov_b32_e32 v119, v181
	v_lshlrev_b32_e32 v122, 16, v116
	v_and_b32_e32 v123, 0xffff0000, v116
	v_lshlrev_b32_e32 v116, 16, v117
	v_and_b32_e32 v117, 0xffff0000, v117
	v_lshlrev_b32_e32 v124, 16, v118
	v_and_b32_e32 v125, 0xffff0000, v118
	v_lshlrev_b32_e32 v118, 16, v119
	v_and_b32_e32 v119, 0xffff0000, v119
	v_pk_add_f32 v[116:117], v[110:111], v[116:117]
	v_pk_add_f32 v[122:123], v[108:109], v[122:123]
	v_pk_add_f32 v[118:119], v[106:107], v[118:119]
	v_pk_add_f32 v[124:125], v[104:105], v[124:125]
	v_cvt_pk_bf16_f32 v104, v122, v123
	v_cvt_pk_bf16_f32 v105, v116, v117
	v_mul_f32_e32 v123, v123, v123
	v_cvt_pk_bf16_f32 v106, v124, v125
	v_cvt_pk_bf16_f32 v107, v118, v119
	v_mov_b32_e32 v108, v182
	v_mov_b32_e32 v109, v183
	v_mov_b32_e32 v110, v184
	v_mov_b32_e32 v111, v185
	v_mul_f32_e32 v117, v117, v117
	v_mul_f32_e32 v125, v125, v125
	v_fmac_f32_e32 v123, v122, v122
	v_fmac_f32_e32 v117, v116, v116
	v_mul_f32_e32 v119, v119, v119
	v_fmac_f32_e32 v125, v124, v124
	v_add_f32_e32 v116, v123, v117
	v_fmac_f32_e32 v119, v118, v118
	v_add_f32_e32 v116, v125, v116
	v_add_f32_e32 v122, v119, v116
	global_store_dwordx4 v[120:121], v[104:107], off
	v_lshlrev_b32_e32 v116, 16, v108
	v_and_b32_e32 v117, 0xffff0000, v108
	v_lshlrev_b32_e32 v108, 16, v109
	v_and_b32_e32 v109, 0xffff0000, v109
	v_lshlrev_b32_e32 v118, 16, v110
	v_and_b32_e32 v119, 0xffff0000, v110
	v_lshlrev_b32_e32 v110, 16, v111
	v_and_b32_e32 v111, 0xffff0000, v111
	v_pk_add_f32 v[102:103], v[102:103], v[108:109]
	v_pk_add_f32 v[100:101], v[100:101], v[116:117]
	v_pk_add_f32 v[108:109], v[98:99], v[110:111]
	v_pk_add_f32 v[110:111], v[96:97], v[118:119]
	v_mul_f32_e32 v96, v101, v101
	v_mul_f32_e32 v97, v103, v103
	v_mul_f32_e32 v98, v111, v111
	v_fmac_f32_e32 v96, v100, v100
	v_fmac_f32_e32 v97, v102, v102
	v_mul_f32_e32 v99, v109, v109
	v_fmac_f32_e32 v98, v110, v110
	v_add_f32_e32 v96, v96, v97
	v_add_f32_e32 v96, v98, v96
	v_fmac_f32_e32 v99, v108, v108
	v_add_f32_e32 v96, v99, v96
	v_add_f32_e32 v96, v122, v96
	ds_bpermute_b32 v97, v114, v96
	v_cvt_pk_bf16_f32 v98, v100, v101
	v_cvt_pk_bf16_f32 v99, v102, v103
	v_cvt_pk_bf16_f32 v100, v110, v111
	v_cvt_pk_bf16_f32 v101, v108, v109
	s_waitcnt lgkmcnt(0)
	v_add_f32_e32 v96, v96, v97
	ds_bpermute_b32 v97, v115, v96
	global_store_dwordx4 v[120:121], v[98:101], off offset:256
	s_and_saveexec_b64 s[14:15], s[6:7]
	s_cbranch_execz .LBB0_1147
	v_lshlrev_b64 v[98:99], 6, v[112:113]
	v_lshl_add_u64 v[98:99], s[20:21], 0, v[98:99]
	v_lshl_add_u64 v[98:99], s[12:13], 2, v[98:99]
	s_lshl_b32 s16, s28, 2
	s_mov_b32 s17, s36
	v_lshl_add_u64 v[98:99], v[98:99], 0, s[16:17]
	s_waitcnt lgkmcnt(0)
	v_add_f32_e32 v96, v96, v97
	global_store_dword v[98:99], v96, off
.LBB0_1147:
	s_or_b64 exec, exec, s[14:15]
	v_or_b32_e32 v96, 32, v130
	s_waitcnt lgkmcnt(0)
	v_ashrrev_i32_e32 v97, 31, v96
	v_lshlrev_b64 v[98:99], 11, v[96:97]
	v_lshl_add_u64 v[98:99], s[22:23], 0, v[98:99]
	v_lshl_add_u64 v[102:103], v[128:129], 1, v[98:99]
	v_mov_b32_e32 v98, v186
	v_mov_b32_e32 v99, v187
	v_mov_b32_e32 v100, v188
	v_mov_b32_e32 v101, v189
	v_lshlrev_b32_e32 v104, 16, v98
	v_and_b32_e32 v105, 0xffff0000, v98
	v_lshlrev_b32_e32 v98, 16, v99
	v_and_b32_e32 v99, 0xffff0000, v99
	v_lshlrev_b32_e32 v106, 16, v100
	v_and_b32_e32 v107, 0xffff0000, v100
	v_lshlrev_b32_e32 v100, 16, v101
	v_and_b32_e32 v101, 0xffff0000, v101
	v_pk_add_f32 v[98:99], v[94:95], v[98:99]
	v_pk_add_f32 v[104:105], v[92:93], v[104:105]
	v_pk_add_f32 v[100:101], v[90:91], v[100:101]
	v_pk_add_f32 v[106:107], v[88:89], v[106:107]
	v_cvt_pk_bf16_f32 v88, v104, v105
	v_cvt_pk_bf16_f32 v89, v98, v99
	v_mul_f32_e32 v105, v105, v105
	v_cvt_pk_bf16_f32 v90, v106, v107
	v_cvt_pk_bf16_f32 v91, v100, v101
	v_mov_b32_e32 v92, v190
	v_mov_b32_e32 v93, v191
	v_mov_b32_e32 v94, v192
	v_mov_b32_e32 v95, v193
	v_mul_f32_e32 v99, v99, v99
	v_mul_f32_e32 v107, v107, v107
	v_fmac_f32_e32 v105, v104, v104
	v_fmac_f32_e32 v99, v98, v98
	v_mul_f32_e32 v101, v101, v101
	v_fmac_f32_e32 v107, v106, v106
	v_add_f32_e32 v98, v105, v99
	v_fmac_f32_e32 v101, v100, v100
	v_add_f32_e32 v98, v107, v98
	v_add_f32_e32 v104, v101, v98
	global_store_dwordx4 v[102:103], v[88:91], off
	v_lshlrev_b32_e32 v98, 16, v92
	v_and_b32_e32 v99, 0xffff0000, v92
	v_lshlrev_b32_e32 v92, 16, v93
	v_and_b32_e32 v93, 0xffff0000, v93
	v_lshlrev_b32_e32 v100, 16, v94
	v_and_b32_e32 v101, 0xffff0000, v94
	v_lshlrev_b32_e32 v94, 16, v95
	v_and_b32_e32 v95, 0xffff0000, v95
	v_pk_add_f32 v[86:87], v[86:87], v[92:93]
	v_pk_add_f32 v[84:85], v[84:85], v[98:99]
	v_pk_add_f32 v[92:93], v[82:83], v[94:95]
	v_pk_add_f32 v[94:95], v[80:81], v[100:101]
	v_mul_f32_e32 v80, v85, v85
	v_mul_f32_e32 v81, v87, v87
	v_mul_f32_e32 v82, v95, v95
	v_fmac_f32_e32 v80, v84, v84
	v_fmac_f32_e32 v81, v86, v86
	v_mul_f32_e32 v83, v93, v93
	v_fmac_f32_e32 v82, v94, v94
	v_add_f32_e32 v80, v80, v81
	v_add_f32_e32 v80, v82, v80
	v_fmac_f32_e32 v83, v92, v92
	v_add_f32_e32 v80, v83, v80
	v_add_f32_e32 v80, v104, v80
	ds_bpermute_b32 v81, v114, v80
	v_cvt_pk_bf16_f32 v82, v84, v85
	v_cvt_pk_bf16_f32 v83, v86, v87
	v_cvt_pk_bf16_f32 v84, v94, v95
	v_cvt_pk_bf16_f32 v85, v92, v93
	s_waitcnt lgkmcnt(0)
	v_add_f32_e32 v80, v80, v81
	ds_bpermute_b32 v81, v115, v80
	global_store_dwordx4 v[102:103], v[82:85], off offset:256
	s_and_saveexec_b64 s[14:15], s[6:7]
	s_cbranch_execz .LBB0_1149
	v_lshlrev_b64 v[82:83], 6, v[96:97]
	v_lshl_add_u64 v[82:83], s[20:21], 0, v[82:83]
	v_lshl_add_u64 v[82:83], s[12:13], 2, v[82:83]
	s_lshl_b32 s16, s28, 2
	s_mov_b32 s17, s36
	v_lshl_add_u64 v[82:83], v[82:83], 0, s[16:17]
	s_waitcnt lgkmcnt(0)
	v_add_f32_e32 v80, v80, v81
	global_store_dword v[82:83], v80, off
; __device__ __forceinline__ unsigned cvt_pk_bf16(float lo, float hi) { unsigned r; asm volatile("v_cvt_pk_bf16_f32 %0, %1, %2" : "=v"(r) : "v"(lo), "v"(hi)); return r; }
; __device__ __forceinline__ void UNPACK8(const u32x4 q, float (&f)[8]) { f[0] = bflo(q.x); f[1] = bfhi(q.x); f[2] = bflo(q.y); f[3] = bfhi(q.y); f[4] = bflo(q.z); f[5] = bfhi(q.z); f[6] = bflo(q.w); f[7] = bfhi(q.w); }
; #define EPI_FOR_ROWS() _Pragma("unroll") for (int ai = 0; ai < 2; ++ai) _Pragma("unroll") for (int m = 0; m < 4; ++m)
;     __device__ __forceinline__ void operator()(const f32x4 (&acc)[2][2][4][2], const Unit& u, int wr, int wc, int fr, int fq) const {
;     ...
;         EPI_FOR_ROWS() {
;             const int row = row0 + ai * 128 + m * 16; float ss = 0.f;
; #pragma unroll
;             for (int bj = 0; bj < 2; ++bj) { const int col = col0 + bj * 128; const size_t off = (size_t)row * 1024 + col;
;                 const u32x4 xw = *(const u32x4*)(xb + off); float xo[8]; UNPACK8(xw, xo);
;                 const f32x4 x0 = (f32x4){xo[0], xo[1], xo[2], xo[3]} + acc[ai][bj][m][0], x1 = (f32x4){xo[4], xo[5], xo[6], xo[7]} + acc[ai][bj][m][1];
;                 ss += (x0[0] * x0[0] + x0[1] * x0[1]) + (x0[2] * x0[2] + x0[3] * x0[3]) + (x1[0] * x1[0] + x1[1] * x1[1]) + (x1[2] * x1[2] + x1[3] * x1[3]);
;                 u32x4 w; w.x = cvt_pk_bf16(x0[0], x0[1]); w.y = cvt_pk_bf16(x0[2], x0[3]); w.z = cvt_pk_bf16(x1[0], x1[1]); w.w = cvt_pk_bf16(x1[2], x1[3]);
;                 *(u32x4*)(xb + off) = w; }
;             ss += __shfl_xor(ss, 16); ss += __shfl_xor(ss, 32);
;             if (fq == 0) ssq[(size_t)row * 16 + u.pn * 4 + wc] = ss;
;         }
.LBB0_1149:
	s_or_b64 exec, exec, s[14:15]
	v_or_b32_e32 v80, 48, v130
	s_waitcnt lgkmcnt(0)
	v_ashrrev_i32_e32 v81, 31, v80
	v_lshlrev_b64 v[82:83], 11, v[80:81]
	v_lshl_add_u64 v[82:83], s[22:23], 0, v[82:83]
	v_lshl_add_u64 v[86:87], v[128:129], 1, v[82:83]
	v_mov_b32_e32 v82, v194
	v_mov_b32_e32 v83, v195
	v_mov_b32_e32 v84, v196
	v_mov_b32_e32 v85, v197
	v_lshlrev_b32_e32 v88, 16, v82
	v_and_b32_e32 v89, 0xffff0000, v82
	v_lshlrev_b32_e32 v82, 16, v83
	v_and_b32_e32 v83, 0xffff0000, v83
	v_lshlrev_b32_e32 v90, 16, v84
	v_and_b32_e32 v91, 0xffff0000, v84
	v_lshlrev_b32_e32 v84, 16, v85
	v_and_b32_e32 v85, 0xffff0000, v85
	v_pk_add_f32 v[82:83], v[78:79], v[82:83]
	v_pk_add_f32 v[88:89], v[76:77], v[88:89]
	v_pk_add_f32 v[84:85], v[74:75], v[84:85]
	v_pk_add_f32 v[90:91], v[72:73], v[90:91]
	v_cvt_pk_bf16_f32 v72, v88, v89
	v_cvt_pk_bf16_f32 v73, v82, v83
	v_mul_f32_e32 v89, v89, v89
	v_cvt_pk_bf16_f32 v74, v90, v91
	v_cvt_pk_bf16_f32 v75, v84, v85
	v_mov_b32_e32 v76, v198
	v_mov_b32_e32 v77, v199
	v_mov_b32_e32 v78, v200
	v_mov_b32_e32 v79, v201
	v_mul_f32_e32 v83, v83, v83
	v_mul_f32_e32 v91, v91, v91
	v_fmac_f32_e32 v89, v88, v88
	v_fmac_f32_e32 v83, v82, v82
	v_mul_f32_e32 v85, v85, v85
	v_fmac_f32_e32 v91, v90, v90
	v_add_f32_e32 v82, v89, v83
	v_fmac_f32_e32 v85, v84, v84
	v_add_f32_e32 v82, v91, v82
	v_add_f32_e32 v88, v85, v82
	global_store_dwordx4 v[86:87], v[72:75], off
	v_lshlrev_b32_e32 v82, 16, v76
	v_and_b32_e32 v83, 0xffff0000, v76
	v_lshlrev_b32_e32 v76, 16, v77
	v_and_b32_e32 v77, 0xffff0000, v77
	v_lshlrev_b32_e32 v84, 16, v78
	v_and_b32_e32 v85, 0xffff0000, v78
	v_lshlrev_b32_e32 v78, 16, v79
	v_and_b32_e32 v79, 0xffff0000, v79
	v_pk_add_f32 v[70:71], v[70:71], v[76:77]
	v_pk_add_f32 v[68:69], v[68:69], v[82:83]
	v_pk_add_f32 v[76:77], v[66:67], v[78:79]
	v_pk_add_f32 v[78:79], v[64:65], v[84:85]
	v_mul_f32_e32 v64, v69, v69
	v_mul_f32_e32 v65, v71, v71
	v_mul_f32_e32 v66, v79, v79
	v_fmac_f32_e32 v64, v68, v68
	v_fmac_f32_e32 v65, v70, v70
	v_mul_f32_e32 v67, v77, v77
	v_fmac_f32_e32 v66, v78, v78
	v_add_f32_e32 v64, v64, v65
	v_add_f32_e32 v64, v66, v64
	v_fmac_f32_e32 v67, v76, v76
	v_add_f32_e32 v64, v67, v64
	v_add_f32_e32 v64, v88, v64
	ds_bpermute_b32 v65, v114, v64
	v_cvt_pk_bf16_f32 v66, v68, v69
	v_cvt_pk_bf16_f32 v67, v70, v71
	v_cvt_pk_bf16_f32 v68, v78, v79
	v_cvt_pk_bf16_f32 v69, v76, v77
	s_waitcnt lgkmcnt(0)
	v_add_f32_e32 v64, v64, v65
	ds_bpermute_b32 v65, v115, v64
	global_store_dwordx4 v[86:87], v[66:69], off offset:256
	s_and_saveexec_b64 s[14:15], s[6:7]
	s_cbranch_execz .LBB0_1151
	v_lshlrev_b64 v[66:67], 6, v[80:81]
	v_lshl_add_u64 v[66:67], s[20:21], 0, v[66:67]
	v_lshl_add_u64 v[66:67], s[12:13], 2, v[66:67]
	s_lshl_b32 s16, s28, 2
	s_mov_b32 s17, s36
	v_lshl_add_u64 v[66:67], v[66:67], 0, s[16:17]
	s_waitcnt lgkmcnt(0)
	v_add_f32_e32 v64, v64, v65
	global_store_dword v[66:67], v64, off
.LBB0_1151:
	s_or_b64 exec, exec, s[14:15]
	v_add_u32_e32 v64, 0x80, v130
	s_waitcnt lgkmcnt(0)
	v_ashrrev_i32_e32 v65, 31, v64
	v_lshlrev_b64 v[66:67], 11, v[64:65]
	v_lshl_add_u64 v[66:67], s[22:23], 0, v[66:67]
	v_lshl_add_u64 v[70:71], v[128:129], 1, v[66:67]
	v_mov_b32_e32 v66, v202
	v_mov_b32_e32 v67, v203
	v_mov_b32_e32 v68, v204
	v_mov_b32_e32 v69, v205
	v_lshlrev_b32_e32 v72, 16, v66
	v_and_b32_e32 v73, 0xffff0000, v66
	v_lshlrev_b32_e32 v66, 16, v67
	v_and_b32_e32 v67, 0xffff0000, v67
	v_lshlrev_b32_e32 v74, 16, v68
	v_and_b32_e32 v75, 0xffff0000, v68
	v_lshlrev_b32_e32 v68, 16, v69
	v_and_b32_e32 v69, 0xffff0000, v69
	v_pk_add_f32 v[66:67], v[62:63], v[66:67]
	v_pk_add_f32 v[72:73], v[60:61], v[72:73]
	v_pk_add_f32 v[68:69], v[58:59], v[68:69]
	v_pk_add_f32 v[74:75], v[56:57], v[74:75]
	v_cvt_pk_bf16_f32 v56, v72, v73
	v_cvt_pk_bf16_f32 v57, v66, v67
	v_mul_f32_e32 v73, v73, v73
	v_cvt_pk_bf16_f32 v58, v74, v75
	v_cvt_pk_bf16_f32 v59, v68, v69
	v_mov_b32_e32 v60, v214
	v_mov_b32_e32 v61, v215
	v_mov_b32_e32 v62, v216
	v_mov_b32_e32 v63, v217
	v_mul_f32_e32 v67, v67, v67
	v_mul_f32_e32 v75, v75, v75
	v_fmac_f32_e32 v73, v72, v72
	v_fmac_f32_e32 v67, v66, v66
	v_mul_f32_e32 v69, v69, v69
	v_fmac_f32_e32 v75, v74, v74
	v_add_f32_e32 v66, v73, v67
	v_fmac_f32_e32 v69, v68, v68
	v_add_f32_e32 v66, v75, v66
	v_add_f32_e32 v72, v69, v66
	global_store_dwordx4 v[70:71], v[56:59], off
	v_lshlrev_b32_e32 v66, 16, v60
	v_and_b32_e32 v67, 0xffff0000, v60
	v_lshlrev_b32_e32 v60, 16, v61
	v_and_b32_e32 v61, 0xffff0000, v61
	v_lshlrev_b32_e32 v68, 16, v62
	v_and_b32_e32 v69, 0xffff0000, v62
	v_lshlrev_b32_e32 v62, 16, v63
	v_and_b32_e32 v63, 0xffff0000, v63
	v_pk_add_f32 v[54:55], v[54:55], v[60:61]
	v_pk_add_f32 v[52:53], v[52:53], v[66:67]
	v_pk_add_f32 v[60:61], v[50:51], v[62:63]
	v_pk_add_f32 v[62:63], v[48:49], v[68:69]
	v_mul_f32_e32 v48, v53, v53
	v_mul_f32_e32 v49, v55, v55
	v_mul_f32_e32 v50, v63, v63
	v_fmac_f32_e32 v48, v52, v52
	v_fmac_f32_e32 v49, v54, v54
	v_mul_f32_e32 v51, v61, v61
	v_fmac_f32_e32 v50, v62, v62
	v_add_f32_e32 v48, v48, v49
	v_add_f32_e32 v48, v50, v48
	v_fmac_f32_e32 v51, v60, v60
	v_add_f32_e32 v48, v51, v48
	v_add_f32_e32 v48, v72, v48
	ds_bpermute_b32 v49, v114, v48
	v_cvt_pk_bf16_f32 v50, v52, v53
	v_cvt_pk_bf16_f32 v51, v54, v55
	v_cvt_pk_bf16_f32 v52, v62, v63
	v_cvt_pk_bf16_f32 v53, v60, v61
	s_waitcnt lgkmcnt(0)
	v_add_f32_e32 v48, v48, v49
	ds_bpermute_b32 v49, v115, v48
	global_store_dwordx4 v[70:71], v[50:53], off offset:256
	s_and_saveexec_b64 s[14:15], s[6:7]
	s_cbranch_execz .LBB0_1153
	v_lshlrev_b64 v[50:51], 6, v[64:65]
	v_lshl_add_u64 v[50:51], s[20:21], 0, v[50:51]
	v_lshl_add_u64 v[50:51], s[12:13], 2, v[50:51]
	s_lshl_b32 s16, s28, 2
	s_mov_b32 s17, s36
	v_lshl_add_u64 v[50:51], v[50:51], 0, s[16:17]
	s_waitcnt lgkmcnt(0)
	v_add_f32_e32 v48, v48, v49
	global_store_dword v[50:51], v48, off
; __device__ __forceinline__ unsigned cvt_pk_bf16(float lo, float hi) { unsigned r; asm volatile("v_cvt_pk_bf16_f32 %0, %1, %2" : "=v"(r) : "v"(lo), "v"(hi)); return r; }
; __device__ __forceinline__ void UNPACK8(const u32x4 q, float (&f)[8]) { f[0] = bflo(q.x); f[1] = bfhi(q.x); f[2] = bflo(q.y); f[3] = bfhi(q.y); f[4] = bflo(q.z); f[5] = bfhi(q.z); f[6] = bflo(q.w); f[7] = bfhi(q.w); }
; #define EPI_FOR_ROWS() _Pragma("unroll") for (int ai = 0; ai < 2; ++ai) _Pragma("unroll") for (int m = 0; m < 4; ++m)
;     __device__ __forceinline__ void operator()(const f32x4 (&acc)[2][2][4][2], const Unit& u, int wr, int wc, int fr, int fq) const {
;     ...
;         EPI_FOR_ROWS() {
;             const int row = row0 + ai * 128 + m * 16; float ss = 0.f;
; #pragma unroll
;             for (int bj = 0; bj < 2; ++bj) { const int col = col0 + bj * 128; const size_t off = (size_t)row * 1024 + col;
;                 const u32x4 xw = *(const u32x4*)(xb + off); float xo[8]; UNPACK8(xw, xo);
;                 const f32x4 x0 = (f32x4){xo[0], xo[1], xo[2], xo[3]} + acc[ai][bj][m][0], x1 = (f32x4){xo[4], xo[5], xo[6], xo[7]} + acc[ai][bj][m][1];
;                 ss += (x0[0] * x0[0] + x0[1] * x0[1]) + (x0[2] * x0[2] + x0[3] * x0[3]) + (x1[0] * x1[0] + x1[1] * x1[1]) + (x1[2] * x1[2] + x1[3] * x1[3]);
;                 u32x4 w; w.x = cvt_pk_bf16(x0[0], x0[1]); w.y = cvt_pk_bf16(x0[2], x0[3]); w.z = cvt_pk_bf16(x1[0], x1[1]); w.w = cvt_pk_bf16(x1[2], x1[3]);
;                 *(u32x4*)(xb + off) = w; }
;             ss += __shfl_xor(ss, 16); ss += __shfl_xor(ss, 32);
;             if (fq == 0) ssq[(size_t)row * 16 + u.pn * 4 + wc] = ss;
;         }
.LBB0_1153:
	s_or_b64 exec, exec, s[14:15]
	v_add_u32_e32 v48, 0x90, v130
	s_waitcnt lgkmcnt(0)
	v_ashrrev_i32_e32 v49, 31, v48
	v_lshlrev_b64 v[50:51], 11, v[48:49]
	v_lshl_add_u64 v[50:51], s[22:23], 0, v[50:51]
	v_lshl_add_u64 v[54:55], v[128:129], 1, v[50:51]
	v_mov_b32_e32 v50, v218
	v_mov_b32_e32 v51, v219
	v_mov_b32_e32 v52, v220
	v_mov_b32_e32 v53, v221
	v_lshlrev_b32_e32 v56, 16, v50
	v_and_b32_e32 v57, 0xffff0000, v50
	v_lshlrev_b32_e32 v50, 16, v51
	v_and_b32_e32 v51, 0xffff0000, v51
	v_lshlrev_b32_e32 v58, 16, v52
	v_and_b32_e32 v59, 0xffff0000, v52
	v_lshlrev_b32_e32 v52, 16, v53
	v_and_b32_e32 v53, 0xffff0000, v53
	v_pk_add_f32 v[50:51], v[46:47], v[50:51]
	v_pk_add_f32 v[56:57], v[44:45], v[56:57]
	v_pk_add_f32 v[52:53], v[42:43], v[52:53]
	v_pk_add_f32 v[58:59], v[40:41], v[58:59]
	v_cvt_pk_bf16_f32 v40, v56, v57
	v_cvt_pk_bf16_f32 v41, v50, v51
	v_mul_f32_e32 v57, v57, v57
	v_cvt_pk_bf16_f32 v42, v58, v59
	v_cvt_pk_bf16_f32 v43, v52, v53
	v_mov_b32_e32 v44, v222
	v_mov_b32_e32 v45, v223
	v_mov_b32_e32 v46, v224
	v_mov_b32_e32 v47, v225
	v_mul_f32_e32 v51, v51, v51
	v_mul_f32_e32 v59, v59, v59
	v_fmac_f32_e32 v57, v56, v56
	v_fmac_f32_e32 v51, v50, v50
	v_mul_f32_e32 v53, v53, v53
	v_fmac_f32_e32 v59, v58, v58
	v_add_f32_e32 v50, v57, v51
	v_fmac_f32_e32 v53, v52, v52
	v_add_f32_e32 v50, v59, v50
	v_add_f32_e32 v56, v53, v50
	global_store_dwordx4 v[54:55], v[40:43], off
	v_lshlrev_b32_e32 v50, 16, v44
	v_and_b32_e32 v51, 0xffff0000, v44
	v_lshlrev_b32_e32 v44, 16, v45
	v_and_b32_e32 v45, 0xffff0000, v45
	v_lshlrev_b32_e32 v52, 16, v46
	v_and_b32_e32 v53, 0xffff0000, v46
	v_lshlrev_b32_e32 v46, 16, v47
	v_and_b32_e32 v47, 0xffff0000, v47
	v_pk_add_f32 v[38:39], v[38:39], v[44:45]
	v_pk_add_f32 v[36:37], v[36:37], v[50:51]
	v_pk_add_f32 v[44:45], v[34:35], v[46:47]
	v_pk_add_f32 v[46:47], v[32:33], v[52:53]
	v_mul_f32_e32 v32, v37, v37
	v_mul_f32_e32 v33, v39, v39
	v_mul_f32_e32 v34, v47, v47
	v_fmac_f32_e32 v32, v36, v36
	v_fmac_f32_e32 v33, v38, v38
	v_mul_f32_e32 v35, v45, v45
	v_fmac_f32_e32 v34, v46, v46
	v_add_f32_e32 v32, v32, v33
	v_add_f32_e32 v32, v34, v32
	v_fmac_f32_e32 v35, v44, v44
	v_add_f32_e32 v32, v35, v32
	v_add_f32_e32 v32, v56, v32
	ds_bpermute_b32 v33, v114, v32
	v_cvt_pk_bf16_f32 v34, v36, v37
	v_cvt_pk_bf16_f32 v35, v38, v39
	v_cvt_pk_bf16_f32 v36, v46, v47
	v_cvt_pk_bf16_f32 v37, v44, v45
	s_waitcnt lgkmcnt(0)
	v_add_f32_e32 v32, v32, v33
	ds_bpermute_b32 v33, v115, v32
	global_store_dwordx4 v[54:55], v[34:37], off offset:256
	s_and_saveexec_b64 s[14:15], s[6:7]
	s_cbranch_execz .LBB0_1155
	v_lshlrev_b64 v[34:35], 6, v[48:49]
	v_lshl_add_u64 v[34:35], s[20:21], 0, v[34:35]
	v_lshl_add_u64 v[34:35], s[12:13], 2, v[34:35]
	s_lshl_b32 s16, s28, 2
	s_mov_b32 s17, s36
	v_lshl_add_u64 v[34:35], v[34:35], 0, s[16:17]
	s_waitcnt lgkmcnt(0)
	v_add_f32_e32 v32, v32, v33
	global_store_dword v[34:35], v32, off
; __device__ __forceinline__ unsigned cvt_pk_bf16(float lo, float hi) { unsigned r; asm volatile("v_cvt_pk_bf16_f32 %0, %1, %2" : "=v"(r) : "v"(lo), "v"(hi)); return r; }
; __device__ __forceinline__ void UNPACK8(const u32x4 q, float (&f)[8]) { f[0] = bflo(q.x); f[1] = bfhi(q.x); f[2] = bflo(q.y); f[3] = bfhi(q.y); f[4] = bflo(q.z); f[5] = bfhi(q.z); f[6] = bflo(q.w); f[7] = bfhi(q.w); }
; #define EPI_FOR_ROWS() _Pragma("unroll") for (int ai = 0; ai < 2; ++ai) _Pragma("unroll") for (int m = 0; m < 4; ++m)
;     __device__ __forceinline__ void operator()(const f32x4 (&acc)[2][2][4][2], const Unit& u, int wr, int wc, int fr, int fq) const {
;     ...
;         EPI_FOR_ROWS() {
;             const int row = row0 + ai * 128 + m * 16; float ss = 0.f;
; #pragma unroll
;             for (int bj = 0; bj < 2; ++bj) { const int col = col0 + bj * 128; const size_t off = (size_t)row * 1024 + col;
;                 const u32x4 xw = *(const u32x4*)(xb + off); float xo[8]; UNPACK8(xw, xo);
;                 const f32x4 x0 = (f32x4){xo[0], xo[1], xo[2], xo[3]} + acc[ai][bj][m][0], x1 = (f32x4){xo[4], xo[5], xo[6], xo[7]} + acc[ai][bj][m][1];
;                 ss += (x0[0] * x0[0] + x0[1] * x0[1]) + (x0[2] * x0[2] + x0[3] * x0[3]) + (x1[0] * x1[0] + x1[1] * x1[1]) + (x1[2] * x1[2] + x1[3] * x1[3]);
;                 u32x4 w; w.x = cvt_pk_bf16(x0[0], x0[1]); w.y = cvt_pk_bf16(x0[2], x0[3]); w.z = cvt_pk_bf16(x1[0], x1[1]); w.w = cvt_pk_bf16(x1[2], x1[3]);
;                 *(u32x4*)(xb + off) = w; }
;             ss += __shfl_xor(ss, 16); ss += __shfl_xor(ss, 32);
;             if (fq == 0) ssq[(size_t)row * 16 + u.pn * 4 + wc] = ss;
;         }
.LBB0_1155:
	s_or_b64 exec, exec, s[14:15]
	v_add_u32_e32 v32, 0xa0, v130
	s_waitcnt lgkmcnt(0)
	v_ashrrev_i32_e32 v33, 31, v32
	v_lshlrev_b64 v[34:35], 11, v[32:33]
	v_lshl_add_u64 v[34:35], s[22:23], 0, v[34:35]
	v_lshl_add_u64 v[38:39], v[128:129], 1, v[34:35]
	v_mov_b32_e32 v34, v226
	v_mov_b32_e32 v35, v227
	v_mov_b32_e32 v36, v228
	v_mov_b32_e32 v37, v229
	v_lshlrev_b32_e32 v40, 16, v34
	v_and_b32_e32 v41, 0xffff0000, v34
	v_lshlrev_b32_e32 v34, 16, v35
	v_and_b32_e32 v35, 0xffff0000, v35
	v_lshlrev_b32_e32 v42, 16, v36
	v_and_b32_e32 v43, 0xffff0000, v36
	v_lshlrev_b32_e32 v36, 16, v37
	v_and_b32_e32 v37, 0xffff0000, v37
	v_pk_add_f32 v[34:35], v[30:31], v[34:35]
	v_pk_add_f32 v[40:41], v[28:29], v[40:41]
	v_pk_add_f32 v[36:37], v[26:27], v[36:37]
	v_pk_add_f32 v[42:43], v[24:25], v[42:43]
	v_cvt_pk_bf16_f32 v24, v40, v41
	v_cvt_pk_bf16_f32 v25, v34, v35
	v_mul_f32_e32 v41, v41, v41
	v_cvt_pk_bf16_f32 v26, v42, v43
	v_cvt_pk_bf16_f32 v27, v36, v37
	v_mov_b32_e32 v28, v230
	v_mov_b32_e32 v29, v231
	v_mov_b32_e32 v30, v232
	v_mov_b32_e32 v31, v233
	v_mul_f32_e32 v35, v35, v35
	v_mul_f32_e32 v43, v43, v43
	v_fmac_f32_e32 v41, v40, v40
	v_fmac_f32_e32 v35, v34, v34
	v_mul_f32_e32 v37, v37, v37
	v_fmac_f32_e32 v43, v42, v42
	v_add_f32_e32 v34, v41, v35
	v_fmac_f32_e32 v37, v36, v36
	v_add_f32_e32 v34, v43, v34
	v_add_f32_e32 v40, v37, v34
	global_store_dwordx4 v[38:39], v[24:27], off
	v_lshlrev_b32_e32 v34, 16, v28
	v_and_b32_e32 v35, 0xffff0000, v28
	v_lshlrev_b32_e32 v28, 16, v29
	v_and_b32_e32 v29, 0xffff0000, v29
	v_lshlrev_b32_e32 v36, 16, v30
	v_and_b32_e32 v37, 0xffff0000, v30
	v_lshlrev_b32_e32 v30, 16, v31
	v_and_b32_e32 v31, 0xffff0000, v31
	v_pk_add_f32 v[22:23], v[22:23], v[28:29]
	v_pk_add_f32 v[20:21], v[20:21], v[34:35]
	v_pk_add_f32 v[28:29], v[18:19], v[30:31]
	v_pk_add_f32 v[30:31], v[16:17], v[36:37]
	v_mul_f32_e32 v16, v21, v21
	v_mul_f32_e32 v17, v23, v23
	v_mul_f32_e32 v18, v31, v31
	v_fmac_f32_e32 v16, v20, v20
	v_fmac_f32_e32 v17, v22, v22
	v_mul_f32_e32 v19, v29, v29
	v_fmac_f32_e32 v18, v30, v30
	v_add_f32_e32 v16, v16, v17
	v_add_f32_e32 v16, v18, v16
	v_fmac_f32_e32 v19, v28, v28
	v_add_f32_e32 v16, v19, v16
	v_add_f32_e32 v16, v40, v16
	ds_bpermute_b32 v17, v114, v16
	v_cvt_pk_bf16_f32 v18, v20, v21
	v_cvt_pk_bf16_f32 v19, v22, v23
	v_cvt_pk_bf16_f32 v20, v30, v31
	v_cvt_pk_bf16_f32 v21, v28, v29
	s_waitcnt lgkmcnt(0)
	v_add_f32_e32 v16, v16, v17
	ds_bpermute_b32 v17, v115, v16
	global_store_dwordx4 v[38:39], v[18:21], off offset:256
	s_and_saveexec_b64 s[14:15], s[6:7]
	s_cbranch_execz .LBB0_1157
	v_lshlrev_b64 v[18:19], 6, v[32:33]
	v_lshl_add_u64 v[18:19], s[20:21], 0, v[18:19]
	v_lshl_add_u64 v[18:19], s[12:13], 2, v[18:19]
	s_lshl_b32 s16, s28, 2
	s_mov_b32 s17, s36
	v_lshl_add_u64 v[18:19], v[18:19], 0, s[16:17]
	s_waitcnt lgkmcnt(0)
	v_add_f32_e32 v16, v16, v17
	global_store_dword v[18:19], v16, off
.LBB0_1157:
	s_or_b64 exec, exec, s[14:15]
	v_add_u32_e32 v16, 0xb0, v130
	s_waitcnt lgkmcnt(0)
	v_ashrrev_i32_e32 v17, 31, v16
	v_lshlrev_b64 v[18:19], 11, v[16:17]
	v_lshl_add_u64 v[18:19], s[22:23], 0, v[18:19]
	v_lshl_add_u64 v[22:23], v[128:129], 1, v[18:19]
	v_mov_b32_e32 v18, v234
	v_mov_b32_e32 v19, v235
	v_mov_b32_e32 v20, v236
	v_mov_b32_e32 v21, v237
	v_lshlrev_b32_e32 v24, 16, v18
	v_and_b32_e32 v25, 0xffff0000, v18
	v_lshlrev_b32_e32 v18, 16, v19
	v_and_b32_e32 v19, 0xffff0000, v19
	v_lshlrev_b32_e32 v26, 16, v20
	v_and_b32_e32 v27, 0xffff0000, v20
	v_lshlrev_b32_e32 v20, 16, v21
	v_and_b32_e32 v21, 0xffff0000, v21
	v_pk_add_f32 v[18:19], v[14:15], v[18:19]
	v_pk_add_f32 v[24:25], v[12:13], v[24:25]
	v_pk_add_f32 v[20:21], v[10:11], v[20:21]
	v_pk_add_f32 v[26:27], v[8:9], v[26:27]
	v_cvt_pk_bf16_f32 v8, v24, v25
	v_cvt_pk_bf16_f32 v9, v18, v19
	v_mul_f32_e32 v25, v25, v25
	v_cvt_pk_bf16_f32 v10, v26, v27
	v_cvt_pk_bf16_f32 v11, v20, v21
	v_mov_b32_e32 v12, v238
	v_mov_b32_e32 v13, v239
	v_mov_b32_e32 v14, v240
	v_mov_b32_e32 v15, v241
	v_mul_f32_e32 v19, v19, v19
	v_mul_f32_e32 v27, v27, v27
	v_fmac_f32_e32 v25, v24, v24
	v_fmac_f32_e32 v19, v18, v18
	v_mul_f32_e32 v21, v21, v21
	v_fmac_f32_e32 v27, v26, v26
	v_add_f32_e32 v18, v25, v19
	v_fmac_f32_e32 v21, v20, v20
	v_add_f32_e32 v18, v27, v18
	v_add_f32_e32 v24, v21, v18
	global_store_dwordx4 v[22:23], v[8:11], off
	v_lshlrev_b32_e32 v18, 16, v12
	v_and_b32_e32 v19, 0xffff0000, v12
	v_lshlrev_b32_e32 v12, 16, v13
	v_and_b32_e32 v13, 0xffff0000, v13
	v_lshlrev_b32_e32 v20, 16, v14
	v_and_b32_e32 v21, 0xffff0000, v14
	v_lshlrev_b32_e32 v14, 16, v15
	v_and_b32_e32 v15, 0xffff0000, v15
	v_pk_add_f32 v[6:7], v[6:7], v[12:13]
	v_pk_add_f32 v[4:5], v[4:5], v[18:19]
	v_pk_add_f32 v[12:13], v[2:3], v[14:15]
	v_pk_add_f32 v[14:15], v[0:1], v[20:21]
	v_mul_f32_e32 v0, v5, v5
	v_mul_f32_e32 v1, v7, v7
	v_mul_f32_e32 v2, v15, v15
	v_fmac_f32_e32 v0, v4, v4
	v_fmac_f32_e32 v1, v6, v6
	v_mul_f32_e32 v3, v13, v13
	v_fmac_f32_e32 v2, v14, v14
	v_add_f32_e32 v0, v0, v1
	v_add_f32_e32 v0, v2, v0
	v_fmac_f32_e32 v3, v12, v12
	v_add_f32_e32 v0, v3, v0
	v_add_f32_e32 v0, v24, v0
	ds_bpermute_b32 v1, v114, v0
	v_cvt_pk_bf16_f32 v2, v4, v5
	v_cvt_pk_bf16_f32 v3, v6, v7
	v_cvt_pk_bf16_f32 v4, v14, v15
	v_cvt_pk_bf16_f32 v5, v12, v13
	s_waitcnt lgkmcnt(0)
	v_add_f32_e32 v0, v0, v1
	ds_bpermute_b32 v1, v115, v0
	global_store_dwordx4 v[22:23], v[2:5], off offset:256
	s_and_saveexec_b64 s[14:15], s[6:7]
	s_cbranch_execz .LBB0_1159
	v_lshlrev_b64 v[2:3], 6, v[16:17]
	v_lshl_add_u64 v[2:3], s[20:21], 0, v[2:3]
	v_lshl_add_u64 v[2:3], s[12:13], 2, v[2:3]
	s_lshl_b32 s12, s28, 2
	s_mov_b32 s13, s36
	v_lshl_add_u64 v[2:3], v[2:3], 0, s[12:13]
	s_waitcnt lgkmcnt(0)
	v_add_f32_e32 v0, v0, v1
	global_store_dword v[2:3], v0, off
